# v_combo11 + PEER gather offsets by one v_mad_u32_u16 per expert id (was shift+mask / bfe+shift-or)
# speedup vs baseline: 1.0068x; 1.0037x over previous
.LBB0_1345:
	s_movk_i32 s81, 0x80
	s_lshl_b32 s0, s48, 7
	s_mov_b32 s80, s48
	s_add_i32 s48, s0, s62
	v_or_b32_e32 v0, s48, v171
	v_ashrrev_i32_e32 v1, 31, v0
	v_lshlrev_b64 v[16:17], 10, v[0:1]
	v_lshlrev_b64 v[0:1], 11, v[0:1]
	v_lshl_add_u64 v[12:13], v[156:157], 0, v[0:1]
	v_mov_b64_e32 v[0:1], v[154:155]
	s_mov_b32 s33, s41

.LBB0_1375:
	v_max_u32_dpp v31, v72, v72 row_ror:1 row_mask:0xf bank_mask:0xf bound_ctrl:1
	v_max_u32_dpp v30, v76, v76 row_ror:1 row_mask:0xf bank_mask:0xf bound_ctrl:1
	v_max_u32_dpp v32, v80, v80 row_ror:1 row_mask:0xf bank_mask:0xf bound_ctrl:1
	v_max_u32_dpp v31, v31, v31 row_ror:2 row_mask:0xf bank_mask:0xf bound_ctrl:1
	v_max_u32_dpp v33, v84, v84 row_ror:1 row_mask:0xf bank_mask:0xf bound_ctrl:1
	v_max_u32_dpp v30, v30, v30 row_ror:2 row_mask:0xf bank_mask:0xf bound_ctrl:1
	v_max_u32_dpp v32, v32, v32 row_ror:2 row_mask:0xf bank_mask:0xf bound_ctrl:1
	v_max_u32_dpp v31, v31, v31 row_ror:4 row_mask:0xf bank_mask:0xf bound_ctrl:1
	v_max_u32_dpp v33, v33, v33 row_ror:2 row_mask:0xf bank_mask:0xf bound_ctrl:1
	v_max_u32_dpp v30, v30, v30 row_ror:4 row_mask:0xf bank_mask:0xf bound_ctrl:1
	v_max_u32_dpp v32, v32, v32 row_ror:4 row_mask:0xf bank_mask:0xf bound_ctrl:1
	v_max_u32_dpp v31, v31, v31 row_ror:8 row_mask:0xf bank_mask:0xf bound_ctrl:1
	v_max_u32_dpp v33, v33, v33 row_ror:4 row_mask:0xf bank_mask:0xf bound_ctrl:1
	v_max_u32_dpp v30, v30, v30 row_ror:8 row_mask:0xf bank_mask:0xf bound_ctrl:1
	v_max_u32_dpp v32, v32, v32 row_ror:8 row_mask:0xf bank_mask:0xf bound_ctrl:1
	v_max_u32_dpp v33, v33, v33 row_ror:8 row_mask:0xf bank_mask:0xf bound_ctrl:1
	v_cmp_eq_u32_e64 s[84:85], v72, v31
	v_cmp_eq_u32_e64 s[86:87], v76, v30
	v_cmp_eq_u32_e64 s[88:89], v80, v32
	v_cmp_eq_u32_e64 s[90:91], v84, v33
	s_mov_b64 exec, s[84:85]
	v_pk_mov_b32 v[72:73], v[72:73], v[74:75] op_sel:[1,0] op_sel_hi:[1,0]
	v_pk_mov_b32 v[74:75], v[74:75], v[70:71] op_sel:[1,0] op_sel_hi:[1,0]
	s_mov_b64 exec, s[86:87]
	v_pk_mov_b32 v[76:77], v[76:77], v[78:79] op_sel:[1,0] op_sel_hi:[1,0]
	v_pk_mov_b32 v[78:79], v[78:79], v[70:71] op_sel:[1,0] op_sel_hi:[1,0]
	s_mov_b64 exec, s[88:89]
	v_pk_mov_b32 v[80:81], v[80:81], v[82:83] op_sel:[1,0] op_sel_hi:[1,0]
	v_pk_mov_b32 v[82:83], v[82:83], v[70:71] op_sel:[1,0] op_sel_hi:[1,0]
	s_mov_b64 exec, s[90:91]
	v_pk_mov_b32 v[84:85], v[84:85], v[86:87] op_sel:[1,0] op_sel_hi:[1,0]
	v_pk_mov_b32 v[86:87], v[86:87], v[70:71] op_sel:[1,0] op_sel_hi:[1,0]
	s_lshl_b64 exec, s[78:79], s40
	s_add_i32 s40, s40, 1
	v_pk_mov_b32 v[4:5], v[32:33], v[32:33] op_sel:[1,0] op_sel_hi:[1,0]
	v_pk_mov_b32 v[6:7], v[30:31], v[30:31] op_sel:[1,0] op_sel_hi:[1,0]
	s_mov_b64 exec, -1
	s_cmp_lg_u32 s40, 8
	s_cbranch_scc1 .LBB0_1375
	v_max_u32_dpp v31, v72, v72 row_ror:1 row_mask:0xf bank_mask:0xf bound_ctrl:1
	v_max_u32_dpp v30, v76, v76 row_ror:1 row_mask:0xf bank_mask:0xf bound_ctrl:1
	v_max_u32_dpp v32, v80, v80 row_ror:1 row_mask:0xf bank_mask:0xf bound_ctrl:1
	v_max_u32_dpp v31, v31, v31 row_ror:2 row_mask:0xf bank_mask:0xf bound_ctrl:1
	v_max_u32_dpp v33, v84, v84 row_ror:1 row_mask:0xf bank_mask:0xf bound_ctrl:1
	v_max_u32_dpp v30, v30, v30 row_ror:2 row_mask:0xf bank_mask:0xf bound_ctrl:1
	v_max_u32_dpp v32, v32, v32 row_ror:2 row_mask:0xf bank_mask:0xf bound_ctrl:1
	v_max_u32_dpp v31, v31, v31 row_ror:4 row_mask:0xf bank_mask:0xf bound_ctrl:1
	v_max_u32_dpp v33, v33, v33 row_ror:2 row_mask:0xf bank_mask:0xf bound_ctrl:1
	v_max_u32_dpp v30, v30, v30 row_ror:4 row_mask:0xf bank_mask:0xf bound_ctrl:1
	v_max_u32_dpp v32, v32, v32 row_ror:4 row_mask:0xf bank_mask:0xf bound_ctrl:1
	v_max_u32_dpp v31, v31, v31 row_ror:8 row_mask:0xf bank_mask:0xf bound_ctrl:1
	v_max_u32_dpp v33, v33, v33 row_ror:4 row_mask:0xf bank_mask:0xf bound_ctrl:1
	v_max_u32_dpp v30, v30, v30 row_ror:8 row_mask:0xf bank_mask:0xf bound_ctrl:1
	v_max_u32_dpp v32, v32, v32 row_ror:8 row_mask:0xf bank_mask:0xf bound_ctrl:1
	v_max_u32_dpp v33, v33, v33 row_ror:8 row_mask:0xf bank_mask:0xf bound_ctrl:1
	v_cmp_eq_u32_e64 s[84:85], v72, v31
	v_cmp_eq_u32_e64 s[86:87], v76, v30
	v_cmp_eq_u32_e64 s[88:89], v80, v32
	v_cmp_eq_u32_e64 s[90:91], v84, v33
	s_mov_b64 exec, s[84:85]
	v_pk_mov_b32 v[72:73], v[72:73], v[74:75] op_sel:[1,0] op_sel_hi:[1,0]
	v_pk_mov_b32 v[74:75], v[74:75], v[70:71] op_sel:[1,0] op_sel_hi:[1,0]
	s_mov_b64 exec, s[86:87]
	v_pk_mov_b32 v[76:77], v[76:77], v[78:79] op_sel:[1,0] op_sel_hi:[1,0]
	v_pk_mov_b32 v[78:79], v[78:79], v[70:71] op_sel:[1,0] op_sel_hi:[1,0]
	s_mov_b64 exec, s[88:89]
	v_pk_mov_b32 v[80:81], v[80:81], v[82:83] op_sel:[1,0] op_sel_hi:[1,0]
	v_pk_mov_b32 v[82:83], v[82:83], v[70:71] op_sel:[1,0] op_sel_hi:[1,0]
	s_mov_b64 exec, s[90:91]
	v_pk_mov_b32 v[84:85], v[84:85], v[86:87] op_sel:[1,0] op_sel_hi:[1,0]
	v_pk_mov_b32 v[86:87], v[86:87], v[70:71] op_sel:[1,0] op_sel_hi:[1,0]
	s_lshl_b64 exec, s[78:79], s40
	s_add_i32 s40, s40, 1
	v_pk_mov_b32 v[4:5], v[32:33], v[32:33] op_sel:[1,0] op_sel_hi:[1,0]
	v_pk_mov_b32 v[6:7], v[30:31], v[30:31] op_sel:[1,0] op_sel_hi:[1,0]
	s_mov_b64 exec, -1
	v_max_u32_dpp v31, v72, v72 row_ror:1 row_mask:0xf bank_mask:0xf bound_ctrl:1
	v_max_u32_dpp v30, v76, v76 row_ror:1 row_mask:0xf bank_mask:0xf bound_ctrl:1
	v_max_u32_dpp v32, v80, v80 row_ror:1 row_mask:0xf bank_mask:0xf bound_ctrl:1
	v_max_u32_dpp v31, v31, v31 row_ror:2 row_mask:0xf bank_mask:0xf bound_ctrl:1
	v_max_u32_dpp v33, v84, v84 row_ror:1 row_mask:0xf bank_mask:0xf bound_ctrl:1
	v_max_u32_dpp v30, v30, v30 row_ror:2 row_mask:0xf bank_mask:0xf bound_ctrl:1
	v_max_u32_dpp v32, v32, v32 row_ror:2 row_mask:0xf bank_mask:0xf bound_ctrl:1
	v_max_u32_dpp v31, v31, v31 row_ror:4 row_mask:0xf bank_mask:0xf bound_ctrl:1
	v_max_u32_dpp v33, v33, v33 row_ror:2 row_mask:0xf bank_mask:0xf bound_ctrl:1
	v_max_u32_dpp v30, v30, v30 row_ror:4 row_mask:0xf bank_mask:0xf bound_ctrl:1
	v_max_u32_dpp v32, v32, v32 row_ror:4 row_mask:0xf bank_mask:0xf bound_ctrl:1
	v_max_u32_dpp v31, v31, v31 row_ror:8 row_mask:0xf bank_mask:0xf bound_ctrl:1
	v_max_u32_dpp v33, v33, v33 row_ror:4 row_mask:0xf bank_mask:0xf bound_ctrl:1
	v_max_u32_dpp v30, v30, v30 row_ror:8 row_mask:0xf bank_mask:0xf bound_ctrl:1
	v_max_u32_dpp v32, v32, v32 row_ror:8 row_mask:0xf bank_mask:0xf bound_ctrl:1
	v_max_u32_dpp v33, v33, v33 row_ror:8 row_mask:0xf bank_mask:0xf bound_ctrl:1
	v_cmp_eq_u32_e64 s[84:85], v72, v31
	v_cmp_eq_u32_e64 s[86:87], v76, v30
	v_cmp_eq_u32_e64 s[88:89], v80, v32
	v_cmp_eq_u32_e64 s[90:91], v84, v33
	s_mov_b64 exec, s[84:85]
	v_pk_mov_b32 v[72:73], v[72:73], v[74:75] op_sel:[1,0] op_sel_hi:[1,0]
	v_pk_mov_b32 v[74:75], v[74:75], v[70:71] op_sel:[1,0] op_sel_hi:[1,0]
	s_mov_b64 exec, s[86:87]
	v_pk_mov_b32 v[76:77], v[76:77], v[78:79] op_sel:[1,0] op_sel_hi:[1,0]
	v_pk_mov_b32 v[78:79], v[78:79], v[70:71] op_sel:[1,0] op_sel_hi:[1,0]
	s_mov_b64 exec, s[88:89]
	v_pk_mov_b32 v[80:81], v[80:81], v[82:83] op_sel:[1,0] op_sel_hi:[1,0]
	v_pk_mov_b32 v[82:83], v[82:83], v[70:71] op_sel:[1,0] op_sel_hi:[1,0]
	s_mov_b64 exec, s[90:91]
	v_pk_mov_b32 v[84:85], v[84:85], v[86:87] op_sel:[1,0] op_sel_hi:[1,0]
	v_pk_mov_b32 v[86:87], v[86:87], v[70:71] op_sel:[1,0] op_sel_hi:[1,0]
	s_lshl_b64 exec, s[78:79], s40
	s_add_i32 s40, s40, 1
	v_pk_mov_b32 v[4:5], v[32:33], v[32:33] op_sel:[1,0] op_sel_hi:[1,0]
	v_pk_mov_b32 v[6:7], v[30:31], v[30:31] op_sel:[1,0] op_sel_hi:[1,0]
	s_mov_b64 exec, -1
	v_max_u32_dpp v31, v72, v72 row_ror:1 row_mask:0xf bank_mask:0xf bound_ctrl:1
	v_max_u32_dpp v30, v76, v76 row_ror:1 row_mask:0xf bank_mask:0xf bound_ctrl:1
	v_max_u32_dpp v32, v80, v80 row_ror:1 row_mask:0xf bank_mask:0xf bound_ctrl:1
	v_max_u32_dpp v31, v31, v31 row_ror:2 row_mask:0xf bank_mask:0xf bound_ctrl:1
	v_max_u32_dpp v33, v84, v84 row_ror:1 row_mask:0xf bank_mask:0xf bound_ctrl:1
	v_max_u32_dpp v30, v30, v30 row_ror:2 row_mask:0xf bank_mask:0xf bound_ctrl:1
	v_max_u32_dpp v32, v32, v32 row_ror:2 row_mask:0xf bank_mask:0xf bound_ctrl:1
	v_max_u32_dpp v31, v31, v31 row_ror:4 row_mask:0xf bank_mask:0xf bound_ctrl:1
	v_max_u32_dpp v33, v33, v33 row_ror:2 row_mask:0xf bank_mask:0xf bound_ctrl:1
	v_max_u32_dpp v30, v30, v30 row_ror:4 row_mask:0xf bank_mask:0xf bound_ctrl:1
	v_max_u32_dpp v32, v32, v32 row_ror:4 row_mask:0xf bank_mask:0xf bound_ctrl:1
	v_max_u32_dpp v31, v31, v31 row_ror:8 row_mask:0xf bank_mask:0xf bound_ctrl:1
	v_max_u32_dpp v33, v33, v33 row_ror:4 row_mask:0xf bank_mask:0xf bound_ctrl:1
	v_max_u32_dpp v30, v30, v30 row_ror:8 row_mask:0xf bank_mask:0xf bound_ctrl:1
	v_max_u32_dpp v32, v32, v32 row_ror:8 row_mask:0xf bank_mask:0xf bound_ctrl:1
	v_max_u32_dpp v33, v33, v33 row_ror:8 row_mask:0xf bank_mask:0xf bound_ctrl:1
	v_cmp_eq_u32_e64 s[84:85], v72, v31
	v_cmp_eq_u32_e64 s[86:87], v76, v30
	v_cmp_eq_u32_e64 s[88:89], v80, v32
	v_cmp_eq_u32_e64 s[90:91], v84, v33
	s_mov_b64 exec, s[84:85]
	v_pk_mov_b32 v[72:73], v[72:73], v[74:75] op_sel:[1,0] op_sel_hi:[1,0]
	v_pk_mov_b32 v[74:75], v[74:75], v[70:71] op_sel:[1,0] op_sel_hi:[1,0]
	s_mov_b64 exec, s[86:87]
	v_pk_mov_b32 v[76:77], v[76:77], v[78:79] op_sel:[1,0] op_sel_hi:[1,0]
	v_pk_mov_b32 v[78:79], v[78:79], v[70:71] op_sel:[1,0] op_sel_hi:[1,0]
	s_mov_b64 exec, s[88:89]
	v_pk_mov_b32 v[80:81], v[80:81], v[82:83] op_sel:[1,0] op_sel_hi:[1,0]
	v_pk_mov_b32 v[82:83], v[82:83], v[70:71] op_sel:[1,0] op_sel_hi:[1,0]
	s_mov_b64 exec, s[90:91]
	v_pk_mov_b32 v[84:85], v[84:85], v[86:87] op_sel:[1,0] op_sel_hi:[1,0]
	v_pk_mov_b32 v[86:87], v[86:87], v[70:71] op_sel:[1,0] op_sel_hi:[1,0]
	s_lshl_b64 exec, s[78:79], s40
	s_add_i32 s40, s40, 1
	v_pk_mov_b32 v[4:5], v[32:33], v[32:33] op_sel:[1,0] op_sel_hi:[1,0]
	v_pk_mov_b32 v[6:7], v[30:31], v[30:31] op_sel:[1,0] op_sel_hi:[1,0]
	s_mov_b64 exec, -1
	v_max_u32_dpp v31, v72, v72 row_ror:1 row_mask:0xf bank_mask:0xf bound_ctrl:1
	v_max_u32_dpp v30, v76, v76 row_ror:1 row_mask:0xf bank_mask:0xf bound_ctrl:1
	v_max_u32_dpp v32, v80, v80 row_ror:1 row_mask:0xf bank_mask:0xf bound_ctrl:1
	v_max_u32_dpp v31, v31, v31 row_ror:2 row_mask:0xf bank_mask:0xf bound_ctrl:1
	v_max_u32_dpp v33, v84, v84 row_ror:1 row_mask:0xf bank_mask:0xf bound_ctrl:1
	v_max_u32_dpp v30, v30, v30 row_ror:2 row_mask:0xf bank_mask:0xf bound_ctrl:1
	v_max_u32_dpp v32, v32, v32 row_ror:2 row_mask:0xf bank_mask:0xf bound_ctrl:1
	v_max_u32_dpp v31, v31, v31 row_ror:4 row_mask:0xf bank_mask:0xf bound_ctrl:1
	v_max_u32_dpp v33, v33, v33 row_ror:2 row_mask:0xf bank_mask:0xf bound_ctrl:1
	v_max_u32_dpp v30, v30, v30 row_ror:4 row_mask:0xf bank_mask:0xf bound_ctrl:1
	v_max_u32_dpp v32, v32, v32 row_ror:4 row_mask:0xf bank_mask:0xf bound_ctrl:1
	v_max_u32_dpp v31, v31, v31 row_ror:8 row_mask:0xf bank_mask:0xf bound_ctrl:1
	v_max_u32_dpp v33, v33, v33 row_ror:4 row_mask:0xf bank_mask:0xf bound_ctrl:1
	v_max_u32_dpp v30, v30, v30 row_ror:8 row_mask:0xf bank_mask:0xf bound_ctrl:1
	v_max_u32_dpp v32, v32, v32 row_ror:8 row_mask:0xf bank_mask:0xf bound_ctrl:1
	v_max_u32_dpp v33, v33, v33 row_ror:8 row_mask:0xf bank_mask:0xf bound_ctrl:1
	v_cmp_eq_u32_e64 s[84:85], v72, v31
	v_cmp_eq_u32_e64 s[86:87], v76, v30
	v_cmp_eq_u32_e64 s[88:89], v80, v32
	v_cmp_eq_u32_e64 s[90:91], v84, v33
	s_mov_b64 exec, s[84:85]
	v_pk_mov_b32 v[72:73], v[72:73], v[74:75] op_sel:[1,0] op_sel_hi:[1,0]
	v_pk_mov_b32 v[74:75], v[74:75], v[70:71] op_sel:[1,0] op_sel_hi:[1,0]
	s_mov_b64 exec, s[86:87]
	v_pk_mov_b32 v[76:77], v[76:77], v[78:79] op_sel:[1,0] op_sel_hi:[1,0]
	v_pk_mov_b32 v[78:79], v[78:79], v[70:71] op_sel:[1,0] op_sel_hi:[1,0]
	s_mov_b64 exec, s[88:89]
	v_pk_mov_b32 v[80:81], v[80:81], v[82:83] op_sel:[1,0] op_sel_hi:[1,0]
	v_pk_mov_b32 v[82:83], v[82:83], v[70:71] op_sel:[1,0] op_sel_hi:[1,0]
	s_mov_b64 exec, s[90:91]
	v_pk_mov_b32 v[84:85], v[84:85], v[86:87] op_sel:[1,0] op_sel_hi:[1,0]
	v_pk_mov_b32 v[86:87], v[86:87], v[70:71] op_sel:[1,0] op_sel_hi:[1,0]
	s_lshl_b64 exec, s[78:79], s40
	s_add_i32 s40, s40, 1
	v_pk_mov_b32 v[4:5], v[32:33], v[32:33] op_sel:[1,0] op_sel_hi:[1,0]
	v_pk_mov_b32 v[6:7], v[30:31], v[30:31] op_sel:[1,0] op_sel_hi:[1,0]
	s_mov_b64 exec, -1
	v_max_u32_dpp v31, v72, v72 row_ror:1 row_mask:0xf bank_mask:0xf bound_ctrl:1
	v_max_u32_dpp v30, v76, v76 row_ror:1 row_mask:0xf bank_mask:0xf bound_ctrl:1
	v_max_u32_dpp v32, v80, v80 row_ror:1 row_mask:0xf bank_mask:0xf bound_ctrl:1
	v_max_u32_dpp v31, v31, v31 row_ror:2 row_mask:0xf bank_mask:0xf bound_ctrl:1
	v_max_u32_dpp v33, v84, v84 row_ror:1 row_mask:0xf bank_mask:0xf bound_ctrl:1
	v_max_u32_dpp v30, v30, v30 row_ror:2 row_mask:0xf bank_mask:0xf bound_ctrl:1
	v_max_u32_dpp v32, v32, v32 row_ror:2 row_mask:0xf bank_mask:0xf bound_ctrl:1
	v_max_u32_dpp v31, v31, v31 row_ror:4 row_mask:0xf bank_mask:0xf bound_ctrl:1
	v_max_u32_dpp v33, v33, v33 row_ror:2 row_mask:0xf bank_mask:0xf bound_ctrl:1
	v_max_u32_dpp v30, v30, v30 row_ror:4 row_mask:0xf bank_mask:0xf bound_ctrl:1
	v_max_u32_dpp v32, v32, v32 row_ror:4 row_mask:0xf bank_mask:0xf bound_ctrl:1
	v_max_u32_dpp v31, v31, v31 row_ror:8 row_mask:0xf bank_mask:0xf bound_ctrl:1
	v_max_u32_dpp v33, v33, v33 row_ror:4 row_mask:0xf bank_mask:0xf bound_ctrl:1
	v_max_u32_dpp v30, v30, v30 row_ror:8 row_mask:0xf bank_mask:0xf bound_ctrl:1
	v_max_u32_dpp v32, v32, v32 row_ror:8 row_mask:0xf bank_mask:0xf bound_ctrl:1
	v_max_u32_dpp v33, v33, v33 row_ror:8 row_mask:0xf bank_mask:0xf bound_ctrl:1
	v_cmp_eq_u32_e64 s[84:85], v72, v31
	v_cmp_eq_u32_e64 s[86:87], v76, v30
	v_cmp_eq_u32_e64 s[88:89], v80, v32
	v_cmp_eq_u32_e64 s[90:91], v84, v33
	s_mov_b64 exec, s[84:85]
	v_pk_mov_b32 v[72:73], v[72:73], v[74:75] op_sel:[1,0] op_sel_hi:[1,0]
	v_pk_mov_b32 v[74:75], v[74:75], v[70:71] op_sel:[1,0] op_sel_hi:[1,0]
	s_mov_b64 exec, s[86:87]
	v_pk_mov_b32 v[76:77], v[76:77], v[78:79] op_sel:[1,0] op_sel_hi:[1,0]
	v_pk_mov_b32 v[78:79], v[78:79], v[70:71] op_sel:[1,0] op_sel_hi:[1,0]
	s_mov_b64 exec, s[88:89]
	v_pk_mov_b32 v[80:81], v[80:81], v[82:83] op_sel:[1,0] op_sel_hi:[1,0]
	v_pk_mov_b32 v[82:83], v[82:83], v[70:71] op_sel:[1,0] op_sel_hi:[1,0]
	s_mov_b64 exec, s[90:91]
	v_pk_mov_b32 v[84:85], v[84:85], v[86:87] op_sel:[1,0] op_sel_hi:[1,0]
	v_pk_mov_b32 v[86:87], v[86:87], v[70:71] op_sel:[1,0] op_sel_hi:[1,0]
	s_lshl_b64 exec, s[78:79], s40
	s_add_i32 s40, s40, 1
	v_pk_mov_b32 v[4:5], v[32:33], v[32:33] op_sel:[1,0] op_sel_hi:[1,0]
	v_pk_mov_b32 v[6:7], v[30:31], v[30:31] op_sel:[1,0] op_sel_hi:[1,0]
	s_mov_b64 exec, -1
	v_max_u32_dpp v31, v72, v72 row_ror:1 row_mask:0xf bank_mask:0xf bound_ctrl:1
	v_max_u32_dpp v30, v76, v76 row_ror:1 row_mask:0xf bank_mask:0xf bound_ctrl:1
	v_max_u32_dpp v32, v80, v80 row_ror:1 row_mask:0xf bank_mask:0xf bound_ctrl:1
	v_max_u32_dpp v31, v31, v31 row_ror:2 row_mask:0xf bank_mask:0xf bound_ctrl:1
	v_max_u32_dpp v33, v84, v84 row_ror:1 row_mask:0xf bank_mask:0xf bound_ctrl:1
	v_max_u32_dpp v30, v30, v30 row_ror:2 row_mask:0xf bank_mask:0xf bound_ctrl:1
	v_max_u32_dpp v32, v32, v32 row_ror:2 row_mask:0xf bank_mask:0xf bound_ctrl:1
	v_max_u32_dpp v31, v31, v31 row_ror:4 row_mask:0xf bank_mask:0xf bound_ctrl:1
	v_max_u32_dpp v33, v33, v33 row_ror:2 row_mask:0xf bank_mask:0xf bound_ctrl:1
	v_max_u32_dpp v30, v30, v30 row_ror:4 row_mask:0xf bank_mask:0xf bound_ctrl:1
	v_max_u32_dpp v32, v32, v32 row_ror:4 row_mask:0xf bank_mask:0xf bound_ctrl:1
	v_max_u32_dpp v31, v31, v31 row_ror:8 row_mask:0xf bank_mask:0xf bound_ctrl:1
	v_max_u32_dpp v33, v33, v33 row_ror:4 row_mask:0xf bank_mask:0xf bound_ctrl:1
	v_max_u32_dpp v30, v30, v30 row_ror:8 row_mask:0xf bank_mask:0xf bound_ctrl:1
	v_max_u32_dpp v32, v32, v32 row_ror:8 row_mask:0xf bank_mask:0xf bound_ctrl:1
	v_max_u32_dpp v33, v33, v33 row_ror:8 row_mask:0xf bank_mask:0xf bound_ctrl:1
	v_cmp_eq_u32_e64 s[84:85], v72, v31
	v_cmp_eq_u32_e64 s[86:87], v76, v30
	v_cmp_eq_u32_e64 s[88:89], v80, v32
	v_cmp_eq_u32_e64 s[90:91], v84, v33
	s_mov_b64 exec, s[84:85]
	v_pk_mov_b32 v[72:73], v[72:73], v[74:75] op_sel:[1,0] op_sel_hi:[1,0]
	s_mov_b64 exec, s[86:87]
	v_pk_mov_b32 v[76:77], v[76:77], v[78:79] op_sel:[1,0] op_sel_hi:[1,0]
	s_mov_b64 exec, s[88:89]
	v_pk_mov_b32 v[80:81], v[80:81], v[82:83] op_sel:[1,0] op_sel_hi:[1,0]
	s_mov_b64 exec, s[90:91]
	v_pk_mov_b32 v[84:85], v[84:85], v[86:87] op_sel:[1,0] op_sel_hi:[1,0]
	s_lshl_b64 exec, s[78:79], s40
	s_add_i32 s40, s40, 1
	v_pk_mov_b32 v[4:5], v[32:33], v[32:33] op_sel:[1,0] op_sel_hi:[1,0]
	v_pk_mov_b32 v[6:7], v[30:31], v[30:31] op_sel:[1,0] op_sel_hi:[1,0]
	s_mov_b64 exec, -1
	v_max_u32_dpp v31, v72, v72 row_ror:1 row_mask:0xf bank_mask:0xf bound_ctrl:1
	v_max_u32_dpp v30, v76, v76 row_ror:1 row_mask:0xf bank_mask:0xf bound_ctrl:1
	v_max_u32_dpp v32, v80, v80 row_ror:1 row_mask:0xf bank_mask:0xf bound_ctrl:1
	v_max_u32_dpp v31, v31, v31 row_ror:2 row_mask:0xf bank_mask:0xf bound_ctrl:1
	v_max_u32_dpp v33, v84, v84 row_ror:1 row_mask:0xf bank_mask:0xf bound_ctrl:1
	v_max_u32_dpp v30, v30, v30 row_ror:2 row_mask:0xf bank_mask:0xf bound_ctrl:1
	v_max_u32_dpp v32, v32, v32 row_ror:2 row_mask:0xf bank_mask:0xf bound_ctrl:1
	v_max_u32_dpp v31, v31, v31 row_ror:4 row_mask:0xf bank_mask:0xf bound_ctrl:1
	v_max_u32_dpp v33, v33, v33 row_ror:2 row_mask:0xf bank_mask:0xf bound_ctrl:1
	v_max_u32_dpp v30, v30, v30 row_ror:4 row_mask:0xf bank_mask:0xf bound_ctrl:1
	v_max_u32_dpp v32, v32, v32 row_ror:4 row_mask:0xf bank_mask:0xf bound_ctrl:1
	v_max_u32_dpp v31, v31, v31 row_ror:8 row_mask:0xf bank_mask:0xf bound_ctrl:1
	v_max_u32_dpp v33, v33, v33 row_ror:4 row_mask:0xf bank_mask:0xf bound_ctrl:1
	v_max_u32_dpp v30, v30, v30 row_ror:8 row_mask:0xf bank_mask:0xf bound_ctrl:1
	v_max_u32_dpp v32, v32, v32 row_ror:8 row_mask:0xf bank_mask:0xf bound_ctrl:1
	v_max_u32_dpp v33, v33, v33 row_ror:8 row_mask:0xf bank_mask:0xf bound_ctrl:1
	v_cmp_eq_u32_e64 s[84:85], v72, v31
	v_cmp_eq_u32_e64 s[86:87], v76, v30
	v_cmp_eq_u32_e64 s[88:89], v80, v32
	v_cmp_eq_u32_e64 s[90:91], v84, v33
	s_mov_b64 exec, s[84:85]
	v_pk_mov_b32 v[72:73], v[72:73], v[74:75] op_sel:[1,0] op_sel_hi:[1,0]
	s_mov_b64 exec, s[86:87]
	v_pk_mov_b32 v[76:77], v[76:77], v[78:79] op_sel:[1,0] op_sel_hi:[1,0]
	s_mov_b64 exec, s[88:89]
	v_pk_mov_b32 v[80:81], v[80:81], v[82:83] op_sel:[1,0] op_sel_hi:[1,0]
	s_mov_b64 exec, s[90:91]
	v_pk_mov_b32 v[84:85], v[84:85], v[86:87] op_sel:[1,0] op_sel_hi:[1,0]
	s_lshl_b64 exec, s[78:79], s40
	s_add_i32 s40, s40, 1
	v_pk_mov_b32 v[4:5], v[32:33], v[32:33] op_sel:[1,0] op_sel_hi:[1,0]
	v_pk_mov_b32 v[6:7], v[30:31], v[30:31] op_sel:[1,0] op_sel_hi:[1,0]
	s_mov_b64 exec, -1
	v_max_u32_dpp v31, v72, v72 row_ror:1 row_mask:0xf bank_mask:0xf bound_ctrl:1
	v_max_u32_dpp v30, v76, v76 row_ror:1 row_mask:0xf bank_mask:0xf bound_ctrl:1
	v_max_u32_dpp v32, v80, v80 row_ror:1 row_mask:0xf bank_mask:0xf bound_ctrl:1
	v_max_u32_dpp v31, v31, v31 row_ror:2 row_mask:0xf bank_mask:0xf bound_ctrl:1
	v_max_u32_dpp v33, v84, v84 row_ror:1 row_mask:0xf bank_mask:0xf bound_ctrl:1
	v_max_u32_dpp v30, v30, v30 row_ror:2 row_mask:0xf bank_mask:0xf bound_ctrl:1
	v_max_u32_dpp v32, v32, v32 row_ror:2 row_mask:0xf bank_mask:0xf bound_ctrl:1
	v_max_u32_dpp v31, v31, v31 row_ror:4 row_mask:0xf bank_mask:0xf bound_ctrl:1
	v_max_u32_dpp v33, v33, v33 row_ror:2 row_mask:0xf bank_mask:0xf bound_ctrl:1
	v_max_u32_dpp v30, v30, v30 row_ror:4 row_mask:0xf bank_mask:0xf bound_ctrl:1
	v_max_u32_dpp v32, v32, v32 row_ror:4 row_mask:0xf bank_mask:0xf bound_ctrl:1
	v_max_u32_dpp v31, v31, v31 row_ror:8 row_mask:0xf bank_mask:0xf bound_ctrl:1
	v_max_u32_dpp v33, v33, v33 row_ror:4 row_mask:0xf bank_mask:0xf bound_ctrl:1
	v_max_u32_dpp v30, v30, v30 row_ror:8 row_mask:0xf bank_mask:0xf bound_ctrl:1
	v_max_u32_dpp v32, v32, v32 row_ror:8 row_mask:0xf bank_mask:0xf bound_ctrl:1
	v_max_u32_dpp v33, v33, v33 row_ror:8 row_mask:0xf bank_mask:0xf bound_ctrl:1
	s_lshl_b64 exec, s[78:79], s40
	v_pk_mov_b32 v[4:5], v[32:33], v[32:33] op_sel:[1,0] op_sel_hi:[1,0]
	v_pk_mov_b32 v[6:7], v[30:31], v[30:31] op_sel:[1,0] op_sel_hi:[1,0]
	s_mov_b64 exec, -1
	v_max_u32_dpp v15, v7, v7 row_ror:1 row_mask:0xf bank_mask:0xf bound_ctrl:1
	v_cmp_lt_i32_e32 vcc, -1, v7
	v_bitop3_b32 v11, v18, s60, v18 bitop3:0xc
	v_max_u32_dpp v15, v15, v15 row_ror:2 row_mask:0xf bank_mask:0xf bound_ctrl:1
	v_cndmask_b32_e64 v14, v217, -1, vcc
	v_bitop3_b32 v14, v14, v7, s59 bitop3:0x78
	v_max_u32_dpp v15, v15, v15 row_ror:4 row_mask:0xf bank_mask:0xf bound_ctrl:1
	v_not_b32_e32 v13, v7
	v_lshrrev_b32_e32 v13, 4, v13
	v_max_u32_dpp v15, v15, v15 row_ror:8 row_mask:0xf bank_mask:0xf bound_ctrl:1
	v_cmp_lt_i32_e32 vcc, -1, v15
	v_and_or_b32 v13, v13, 15, v195
	v_lshlrev_b32_e32 v13, 2, v13
	v_cndmask_b32_e64 v18, v217, -1, vcc
	v_bitop3_b32 v15, v18, v15, s59 bitop3:0x78
	v_sub_f32_e32 v14, v14, v15
	v_mul_f32_e32 v14, 0x3fb8aa3b, v14
	v_exp_f32_e32 v14, v14
	ds_bpermute_b32 v11, v13, v11
	v_bitop3_b32 v7, v7, v195, 15 bitop3:0xce
	v_bitop3_b32 v0, v0, s60, v0 bitop3:0xc
	v_add_f32_dpp v13, v14, v14 row_ror:1 row_mask:0xf bank_mask:0xf bound_ctrl:1
	v_lshlrev_b32_e32 v7, 2, v7
	ds_bpermute_b32 v0, v7, v0
	v_add_f32_dpp v13, v13, v13 row_ror:2 row_mask:0xf bank_mask:0xf bound_ctrl:1
	v_bitop3_b32 v10, v19, s60, v19 bitop3:0xc
	v_bitop3_b32 v9, v20, s60, v20 bitop3:0xc
	v_add_f32_dpp v13, v13, v13 row_ror:4 row_mask:0xf bank_mask:0xf bound_ctrl:1
	v_lshl_or_b32 v12, s33, 4, v171
	s_waitcnt lgkmcnt(0)
	v_lshl_add_u32 v0, v11, 7, v0
	v_add_f32_dpp v13, v13, v13 row_ror:8 row_mask:0xf bank_mask:0xf bound_ctrl:1
	v_div_scale_f32 v15, s[0:1], v13, v13, v14
	v_rcp_f32_e32 v18, v15
	v_bitop3_b32 v1, v1, s60, v1 bitop3:0xc
	v_bitop3_b32 v2, v2, s60, v2 bitop3:0xc
	v_bitop3_b32 v3, v3, s60, v3 bitop3:0xc
	v_fma_f32 v7, -v15, v18, 1.0
	v_fmac_f32_e32 v18, v7, v18
	v_div_scale_f32 v7, vcc, v14, v13, v14
	v_mul_f32_e32 v19, v7, v18
	v_fma_f32 v20, -v15, v19, v7
	v_fmac_f32_e32 v19, v20, v18
	v_fma_f32 v7, -v15, v19, v7
	v_div_fmas_f32 v7, v7, v18, v19
	v_div_fixup_f32 v7, v7, v13, v14
	v_or_b32_e32 v13, v12, v183
	v_lshl_add_u32 v11, v13, 1, s63
	v_cvt_f16_f32_e32 v7, v7
	v_max_u32_dpp v13, v6, v6 row_ror:1 row_mask:0xf bank_mask:0xf bound_ctrl:1
	v_cmp_lt_i32_e32 vcc, -1, v6
	ds_write_b16 v11, v0
	ds_write_b16 v11, v7 offset:32768
	v_max_u32_dpp v13, v13, v13 row_ror:2 row_mask:0xf bank_mask:0xf bound_ctrl:1
	v_cndmask_b32_e64 v7, v217, -1, vcc
	v_bitop3_b32 v7, v7, v6, s59 bitop3:0x78
	v_max_u32_dpp v13, v13, v13 row_ror:4 row_mask:0xf bank_mask:0xf bound_ctrl:1
	v_not_b32_e32 v0, v6
	v_lshrrev_b32_e32 v0, 4, v0
	v_max_u32_dpp v13, v13, v13 row_ror:8 row_mask:0xf bank_mask:0xf bound_ctrl:1
	v_cmp_lt_i32_e32 vcc, -1, v13
	v_and_or_b32 v0, v0, 15, v195
	v_lshlrev_b32_e32 v0, 2, v0
	v_cndmask_b32_e64 v14, v217, -1, vcc
	v_bitop3_b32 v13, v14, v13, s59 bitop3:0x78
	v_sub_f32_e32 v7, v7, v13
	v_mul_f32_e32 v7, 0x3fb8aa3b, v7
	v_exp_f32_e32 v7, v7
	ds_bpermute_b32 v0, v0, v10
	v_bitop3_b32 v6, v6, v195, 15 bitop3:0xce
	v_lshlrev_b32_e32 v6, 2, v6
	v_add_f32_dpp v10, v7, v7 row_ror:1 row_mask:0xf bank_mask:0xf bound_ctrl:1
	ds_bpermute_b32 v1, v6, v1
	v_bitop3_b32 v8, v21, s60, v21 bitop3:0xc
	v_add_f32_dpp v10, v10, v10 row_ror:2 row_mask:0xf bank_mask:0xf bound_ctrl:1
	s_waitcnt lgkmcnt(0)
	v_lshl_add_u32 v0, v0, 7, v1
	v_add_f32_dpp v10, v10, v10 row_ror:4 row_mask:0xf bank_mask:0xf bound_ctrl:1
	ds_write_b16 v11, v0 offset:256
	v_not_b32_e32 v1, v5
	v_add_f32_dpp v10, v10, v10 row_ror:8 row_mask:0xf bank_mask:0xf bound_ctrl:1
	v_div_scale_f32 v13, s[0:1], v10, v10, v7
	v_rcp_f32_e32 v14, v13
	v_lshrrev_b32_e32 v1, 4, v1
	v_and_or_b32 v1, v1, 15, v195
	v_lshlrev_b32_e32 v1, 2, v1
	v_fma_f32 v6, -v13, v14, 1.0
	v_fmac_f32_e32 v14, v6, v14
	v_div_scale_f32 v6, vcc, v7, v10, v7
	v_mul_f32_e32 v15, v6, v14
	v_fma_f32 v18, -v13, v15, v6
	v_fmac_f32_e32 v15, v18, v14
	v_fma_f32 v6, -v13, v15, v6
	v_div_fmas_f32 v6, v6, v14, v15
	v_div_fixup_f32 v6, v6, v10, v7
	v_max_u32_dpp v7, v5, v5 row_ror:1 row_mask:0xf bank_mask:0xf bound_ctrl:1
	v_cmp_lt_i32_e32 vcc, -1, v5
	v_cvt_f16_f32_e32 v0, v6
	v_max_u32_dpp v7, v7, v7 row_ror:2 row_mask:0xf bank_mask:0xf bound_ctrl:1
	v_cndmask_b32_e64 v6, v217, -1, vcc
	v_bitop3_b32 v6, v6, v5, s59 bitop3:0x78
	v_max_u32_dpp v7, v7, v7 row_ror:4 row_mask:0xf bank_mask:0xf bound_ctrl:1
	ds_bpermute_b32 v1, v1, v9
	v_bitop3_b32 v5, v5, v195, 15 bitop3:0xce
	v_max_u32_dpp v7, v7, v7 row_ror:8 row_mask:0xf bank_mask:0xf bound_ctrl:1
	v_cmp_lt_i32_e32 vcc, -1, v7
	v_lshlrev_b32_e32 v5, 2, v5
	ds_bpermute_b32 v2, v5, v2
	v_cndmask_b32_e64 v10, v217, -1, vcc
	v_bitop3_b32 v7, v10, v7, s59 bitop3:0x78
	v_sub_f32_e32 v6, v6, v7
	v_mul_f32_e32 v6, 0x3fb8aa3b, v6
	v_exp_f32_e32 v6, v6
	ds_write_b16 v11, v0 offset:33024
	s_waitcnt lgkmcnt(1)
	v_lshl_add_u32 v0, v1, 7, v2
	v_max_u32_dpp v2, v4, v4 row_ror:1 row_mask:0xf bank_mask:0xf bound_ctrl:1
	v_add_f32_dpp v7, v6, v6 row_ror:1 row_mask:0xf bank_mask:0xf bound_ctrl:1
	s_nop 0
	v_max_u32_dpp v2, v2, v2 row_ror:2 row_mask:0xf bank_mask:0xf bound_ctrl:1
	v_add_f32_dpp v7, v7, v7 row_ror:2 row_mask:0xf bank_mask:0xf bound_ctrl:1
	s_nop 0
	v_max_u32_dpp v2, v2, v2 row_ror:4 row_mask:0xf bank_mask:0xf bound_ctrl:1
	v_add_f32_dpp v7, v7, v7 row_ror:4 row_mask:0xf bank_mask:0xf bound_ctrl:1
	s_nop 0
	v_max_u32_dpp v2, v2, v2 row_ror:8 row_mask:0xf bank_mask:0xf bound_ctrl:1
	v_add_f32_dpp v7, v7, v7 row_ror:8 row_mask:0xf bank_mask:0xf bound_ctrl:1
	v_div_scale_f32 v9, s[0:1], v7, v7, v6
	v_rcp_f32_e32 v10, v9
	s_nop 0
	v_fma_f32 v5, -v9, v10, 1.0
	v_fmac_f32_e32 v10, v5, v10
	v_div_scale_f32 v5, vcc, v6, v7, v6
	v_mul_f32_e32 v13, v5, v10
	v_fma_f32 v14, -v9, v13, v5
	v_fmac_f32_e32 v13, v14, v10
	v_fma_f32 v5, -v9, v13, v5
	v_div_fmas_f32 v5, v5, v10, v13
	v_div_fixup_f32 v5, v5, v7, v6
	v_cvt_f16_f32_e32 v5, v5
	v_cmp_lt_i32_e32 vcc, -1, v4
	ds_write_b16 v11, v0 offset:512
	ds_write_b16 v11, v5 offset:33280
	v_cndmask_b32_e64 v1, v217, -1, vcc
	v_cmp_lt_i32_e32 vcc, -1, v2
	v_bitop3_b32 v1, v1, v4, s59 bitop3:0x78
	v_not_b32_e32 v0, v4
	v_cndmask_b32_e64 v5, v217, -1, vcc
	v_bitop3_b32 v2, v5, v2, s59 bitop3:0x78
	v_sub_f32_e32 v1, v1, v2
	v_mul_f32_e32 v1, 0x3fb8aa3b, v1
	v_exp_f32_e32 v1, v1
	v_bitop3_b32 v4, v4, v195, 15 bitop3:0xce
	v_lshlrev_b32_e32 v4, 2, v4
	v_lshrrev_b32_e32 v0, 4, v0
	v_add_f32_dpp v2, v1, v1 row_ror:1 row_mask:0xf bank_mask:0xf bound_ctrl:1
	ds_bpermute_b32 v3, v4, v3
	v_and_or_b32 v0, v0, 15, v195
	v_add_f32_dpp v2, v2, v2 row_ror:2 row_mask:0xf bank_mask:0xf bound_ctrl:1
	v_lshlrev_b32_e32 v0, 2, v0
	ds_bpermute_b32 v0, v0, v8
	v_add_f32_dpp v2, v2, v2 row_ror:4 row_mask:0xf bank_mask:0xf bound_ctrl:1
	s_waitcnt lgkmcnt(0)
	v_lshl_add_u32 v0, v0, 7, v3
	v_add_f32_dpp v2, v2, v2 row_ror:8 row_mask:0xf bank_mask:0xf bound_ctrl:1
	v_div_scale_f32 v5, s[0:1], v2, v2, v1
	v_rcp_f32_e32 v6, v5
	s_add_i32 s0, s33, 1
	s_cmp_lg_u32 s33, 7
	s_cselect_b32 s1, s0, 7
	v_fma_f32 v4, -v5, v6, 1.0
	v_fmac_f32_e32 v6, v4, v6
	v_div_scale_f32 v4, vcc, v1, v2, v1
	v_mul_f32_e32 v7, v4, v6
	v_fma_f32 v8, -v5, v7, v4
	v_fmac_f32_e32 v7, v8, v6
	v_fma_f32 v4, -v5, v7, v4
	v_div_fmas_f32 v4, v4, v6, v7
	v_div_fixup_f32 v1, v4, v2, v1
	v_add_u32_e32 v2, v12, v182
	v_cvt_f16_f32_e32 v1, v1
	v_lshl_or_b32 v2, v2, 1, v218
	s_lshl_b32 s40, s1, 16
	v_add_u32_e32 v2, s63, v2
	s_cmp_lt_u32 s1, 4
	ds_write_b16 v2, v0
	ds_write_b16 v2, v1 offset:32768
	v_lshl_add_u64 v[0:1], v[154:155], 0, s[40:41]
	s_cselect_b32 s33, s3, s56
	s_cselect_b32 s40, s2, s55
	v_mov_b32_e32 v2, s40
	v_mov_b32_e32 v3, s33
	s_lshl_b32 s1, s1, 9
	v_lshl_add_u64 v[2:3], v[16:17], 1, v[2:3]
	s_and_b32 s40, s1, 0x600
	v_lshl_add_u64 v[2:3], v[2:3], 0, s[40:41]
	v_lshl_add_u64 v[12:13], v[2:3], 0, v[148:149]
	s_cmp_eq_u32 s0, 8
	s_mov_b32 s33, s0
	s_cbranch_scc0 .LBB0_1346
	s_waitcnt lgkmcnt(0)
	s_barrier
	ds_read_b128 v[0:3], v185
	ds_read_b128 v[40:43], v185 offset:16
	s_ashr_i32 s49, s48, 31
	s_lshl_b64 s[0:1], s[48:49], 10
	v_lshl_add_u64 v[144:145], v[152:153], 0, s[0:1]
	s_waitcnt lgkmcnt(1)
	v_lshlrev_b32_e32 v4, 7, v0
	v_mad_u32_u16 v0, v0, s81, v150 op_sel:[1,0,0,0]
	v_and_or_b32 v64, v4, s68, v150
	v_mad_u32_u16 v4, v1, s81, v150
	global_load_dwordx4 v[60:63], v0, s[26:27]
	global_load_dwordx4 v[56:59], v4, s[26:27]
	v_mad_u32_u16 v0, v1, s81, v150 op_sel:[1,0,0,0]
	v_mad_u32_u16 v1, v2, s81, v150
	global_load_dwordx4 v[52:55], v0, s[26:27]
	global_load_dwordx4 v[48:51], v1, s[26:27]
	v_mad_u32_u16 v0, v2, s81, v150 op_sel:[1,0,0,0]
	v_mad_u32_u16 v1, v3, s81, v150
	global_load_dwordx4 v[44:47], v0, s[26:27]
	global_load_dwordx4 v[36:39], v1, s[26:27]
	v_mad_u32_u16 v0, v3, s81, v150 op_sel:[1,0,0,0]
	s_waitcnt lgkmcnt(0)
	v_mad_u32_u16 v1, v40, s81, v150
	global_load_dwordx4 v[32:35], v0, s[26:27]
	global_load_dwordx4 v[28:31], v1, s[26:27]
	v_mad_u32_u16 v0, v40, s81, v150 op_sel:[1,0,0,0]
	v_mad_u32_u16 v1, v41, s81, v150
	global_load_dwordx4 v[24:27], v0, s[26:27]
	global_load_dwordx4 v[20:23], v1, s[26:27]
	v_mad_u32_u16 v0, v41, s81, v150 op_sel:[1,0,0,0]
	v_mad_u32_u16 v1, v42, s81, v150
	global_load_dwordx4 v[16:19], v0, s[26:27]
	global_load_dwordx4 v[12:15], v1, s[26:27]
	v_mad_u32_u16 v0, v42, s81, v150 op_sel:[1,0,0,0]
	v_mad_u32_u16 v1, v43, s81, v150
	global_load_dwordx4 v[8:11], v0, s[26:27]
	global_load_dwordx4 v[4:7], v1, s[26:27]
	v_mad_u32_u16 v0, v43, s81, v150 op_sel:[1,0,0,0]
	global_load_dwordx4 v[0:3], v0, s[26:27]
	s_nop 0
	global_load_dwordx4 v[64:67], v64, s[26:27]
	s_nop 0
	global_load_dwordx4 v[40:43], v[144:145], off
	ds_read_b128 v[140:143], v185 offset:256
	ds_read_b128 v[136:139], v185 offset:272
	s_mov_b32 s76, 0
	s_branch .LBB0_1379

.LBB0_1379:
	s_lshr_b32 s52, s76, 4
	s_lshl_b32 s33, s52, 21
	s_add_u32 s50, s26, s33
	s_waitcnt lgkmcnt(1)
	v_mad_u32_u16 v68, v140, s81, v150
	v_mad_u32_u16 v69, v140, s81, v150 op_sel:[1,0,0,0]
	s_addc_u32 s51, s27, 0
	global_load_dwordx4 v[132:135], v68, s[50:51]
	global_load_dwordx4 v[128:131], v69, s[50:51]
	v_mad_u32_u16 v68, v141, s81, v150
	v_mad_u32_u16 v69, v141, s81, v150 op_sel:[1,0,0,0]
	global_load_dwordx4 v[124:127], v68, s[50:51]
	global_load_dwordx4 v[120:123], v69, s[50:51]
	v_mad_u32_u16 v68, v142, s81, v150
	v_mad_u32_u16 v69, v142, s81, v150 op_sel:[1,0,0,0]
	global_load_dwordx4 v[116:119], v68, s[50:51]
	global_load_dwordx4 v[112:115], v69, s[50:51]
	v_mad_u32_u16 v68, v143, s81, v150
	v_mad_u32_u16 v69, v143, s81, v150 op_sel:[1,0,0,0]
	global_load_dwordx4 v[108:111], v68, s[50:51]
	global_load_dwordx4 v[104:107], v69, s[50:51]
	s_waitcnt lgkmcnt(0)
	v_mad_u32_u16 v68, v136, s81, v150
	v_mad_u32_u16 v69, v136, s81, v150 op_sel:[1,0,0,0]
	global_load_dwordx4 v[100:103], v68, s[50:51]
	global_load_dwordx4 v[96:99], v69, s[50:51]
	v_mad_u32_u16 v68, v137, s81, v150
	v_mad_u32_u16 v69, v137, s81, v150 op_sel:[1,0,0,0]
	global_load_dwordx4 v[92:95], v68, s[50:51]
	global_load_dwordx4 v[88:91], v69, s[50:51]
	v_mad_u32_u16 v68, v138, s81, v150
	v_mad_u32_u16 v69, v138, s81, v150 op_sel:[1,0,0,0]
	s_add_i32 s33, s76, 2
	s_cmpk_gt_u32 s76, 0x7d
	global_load_dwordx4 v[84:87], v68, s[50:51]
	global_load_dwordx4 v[76:79], v69, s[50:51]
	v_mad_u32_u16 v68, v139, s81, v150
	v_mad_u32_u16 v69, v139, s81, v150 op_sel:[1,0,0,0]
	s_cselect_b64 s[48:49], -1, 0
	s_cmpk_lt_u32 s76, 0x7e
	s_cselect_b32 s77, s33, 0x7f
	global_load_dwordx4 v[72:75], v68, s[50:51]
	s_nop 0
	global_load_dwordx4 v[68:71], v69, s[50:51]
	s_and_b32 s50, s76, 14
	s_or_b32 s45, s50, 1
	s_lshl_b32 s40, s45, 10
	v_lshl_add_u64 v[80:81], v[144:145], 0, s[40:41]
	s_lshl_b32 s40, s52, 7
	v_lshl_add_u64 v[80:81], v[80:81], 0, s[40:41]
	global_load_dwordx4 v[80:83], v[80:81], off
	s_and_b32 s40, s77, 15
	v_lshl_add_u32 v136, s40, 8, v185
	ds_read_b128 v[140:143], v136
	ds_read_b128 v[136:139], v136 offset:16
	v_mov_b32_e32 v146, 0
	s_waitcnt vmcnt(17)
	v_dot4c_i32_i8_e32 v146, v40, v64
	v_mov_b32_e32 v64, 0
	v_dot4c_i32_i8_e32 v64, v40, v60
	v_mov_b32_e32 v60, 0
	v_dot4c_i32_i8_e32 v60, v40, v56
	v_mov_b32_e32 v56, 0
	v_dot4c_i32_i8_e32 v56, v40, v52
	v_mov_b32_e32 v52, 0
	v_dot4c_i32_i8_e32 v52, v40, v48
	v_mov_b32_e32 v48, 0
	v_dot4c_i32_i8_e32 v48, v40, v44
	v_mov_b32_e32 v44, 0
	v_dot4c_i32_i8_e32 v44, v40, v36
	v_mov_b32_e32 v36, 0
	v_dot4c_i32_i8_e32 v36, v40, v32
	v_mov_b32_e32 v32, 0
	v_dot4c_i32_i8_e32 v32, v40, v28
	v_mov_b32_e32 v28, 0
	v_dot4c_i32_i8_e32 v28, v40, v24
	v_mov_b32_e32 v24, 0
	v_dot4c_i32_i8_e32 v24, v40, v20
	v_mov_b32_e32 v20, 0
	v_dot4c_i32_i8_e32 v20, v40, v16
	v_mov_b32_e32 v16, 0
	v_dot4c_i32_i8_e32 v16, v40, v12
	v_mov_b32_e32 v12, 0
	v_dot4c_i32_i8_e32 v64, v41, v61
	v_dot4c_i32_i8_e32 v12, v40, v8
	v_mov_b32_e32 v8, 0
	v_dot4c_i32_i8_e32 v146, v41, v65
	v_dot4c_i32_i8_e32 v64, v42, v62
	v_dot4c_i32_i8_e32 v32, v41, v29
	v_dot4c_i32_i8_e32 v28, v41, v25
	v_dot4c_i32_i8_e32 v8, v40, v4
	v_mov_b32_e32 v4, 0
	v_dot4c_i32_i8_e32 v146, v42, v66
	v_dot4c_i32_i8_e32 v64, v43, v63
	v_dot4c_i32_i8_e32 v60, v41, v57
	v_dot4c_i32_i8_e32 v32, v42, v30
	v_dot4c_i32_i8_e32 v28, v42, v26
	v_dot4c_i32_i8_e32 v24, v41, v21
	v_dot4c_i32_i8_e32 v16, v41, v13
	v_dot4c_i32_i8_e32 v12, v41, v9
	v_dot4c_i32_i8_e32 v4, v40, v0
	v_dot4c_i32_i8_e32 v146, v43, v67
	v_dot4c_i32_i8_e32 v60, v42, v58
	v_dot4c_i32_i8_e32 v56, v41, v53
	v_dot4c_i32_i8_e32 v32, v43, v31
	v_dot4c_i32_i8_e32 v28, v43, v27
	v_dot4c_i32_i8_e32 v24, v42, v22
	v_dot4c_i32_i8_e32 v20, v41, v17
	v_dot4c_i32_i8_e32 v16, v42, v14
	v_dot4c_i32_i8_e32 v12, v42, v10
	v_dot4c_i32_i8_e32 v4, v41, v1
	v_add_u32_dpp v1, v64, v64 quad_perm:[1,0,3,2] row_mask:0xf bank_mask:0xf bound_ctrl:1
	v_dot4c_i32_i8_e32 v60, v43, v59
	v_dot4c_i32_i8_e32 v56, v42, v54
	v_dot4c_i32_i8_e32 v52, v41, v49
	v_dot4c_i32_i8_e32 v24, v43, v23
	v_dot4c_i32_i8_e32 v20, v42, v18
	v_dot4c_i32_i8_e32 v16, v43, v15
	v_dot4c_i32_i8_e32 v12, v43, v11
	v_add_u32_dpp v0, v146, v146 quad_perm:[1,0,3,2] row_mask:0xf bank_mask:0xf bound_ctrl:1
	v_add_u32_dpp v10, v32, v32 quad_perm:[1,0,3,2] row_mask:0xf bank_mask:0xf bound_ctrl:1
	v_add_u32_dpp v11, v28, v28 quad_perm:[1,0,3,2] row_mask:0xf bank_mask:0xf bound_ctrl:1
	v_add_u32_dpp v1, v1, v1 quad_perm:[2,3,0,1] row_mask:0xf bank_mask:0xf bound_ctrl:1
	v_dot4c_i32_i8_e32 v56, v43, v55
	v_dot4c_i32_i8_e32 v52, v42, v50
	v_dot4c_i32_i8_e32 v48, v41, v45
	v_dot4c_i32_i8_e32 v20, v43, v19
	v_dot4c_i32_i8_e32 v4, v42, v2
	v_add_u32_dpp v2, v60, v60 quad_perm:[1,0,3,2] row_mask:0xf bank_mask:0xf bound_ctrl:1
	v_add_u32_dpp v13, v24, v24 quad_perm:[1,0,3,2] row_mask:0xf bank_mask:0xf bound_ctrl:1
	v_add_u32_dpp v15, v16, v16 quad_perm:[1,0,3,2] row_mask:0xf bank_mask:0xf bound_ctrl:1
	v_add_u32_dpp v0, v0, v0 quad_perm:[2,3,0,1] row_mask:0xf bank_mask:0xf bound_ctrl:1
	v_add_u32_dpp v10, v10, v10 quad_perm:[2,3,0,1] row_mask:0xf bank_mask:0xf bound_ctrl:1
	v_add_u32_dpp v11, v11, v11 quad_perm:[2,3,0,1] row_mask:0xf bank_mask:0xf bound_ctrl:1
	v_mov_b32_dpp v16, v1 row_half_mirror row_mask:0xf bank_mask:0xf bound_ctrl:1
	v_dot4c_i32_i8_e32 v52, v43, v51
	v_dot4c_i32_i8_e32 v48, v42, v46
	v_dot4c_i32_i8_e32 v44, v41, v37
	v_dot4c_i32_i8_e32 v8, v41, v5
	v_dot4c_i32_i8_e32 v4, v43, v3
	v_add_u32_dpp v3, v56, v56 quad_perm:[1,0,3,2] row_mask:0xf bank_mask:0xf bound_ctrl:1
	v_add_u32_dpp v14, v20, v20 quad_perm:[1,0,3,2] row_mask:0xf bank_mask:0xf bound_ctrl:1
	v_add_u32_dpp v2, v2, v2 quad_perm:[2,3,0,1] row_mask:0xf bank_mask:0xf bound_ctrl:1
	v_add_u32_dpp v13, v13, v13 quad_perm:[2,3,0,1] row_mask:0xf bank_mask:0xf bound_ctrl:1
	v_add_u32_dpp v0, v0, v0 row_half_mirror row_mask:0xf bank_mask:0xf bound_ctrl:1
	v_add_u32_dpp v10, v10, v10 row_half_mirror row_mask:0xf bank_mask:0xf bound_ctrl:1
	v_add_u32_dpp v11, v11, v11 row_half_mirror row_mask:0xf bank_mask:0xf bound_ctrl:1
	v_add_u32_e32 v1, v16, v1
	v_dot4c_i32_i8_e32 v48, v43, v47
	v_dot4c_i32_i8_e32 v44, v42, v38
	v_dot4c_i32_i8_e32 v36, v41, v33
	v_dot4c_i32_i8_e32 v8, v42, v6
	v_add_u32_dpp v5, v52, v52 quad_perm:[1,0,3,2] row_mask:0xf bank_mask:0xf bound_ctrl:1
	v_add_u32_dpp v3, v3, v3 quad_perm:[2,3,0,1] row_mask:0xf bank_mask:0xf bound_ctrl:1
	v_add_u32_dpp v14, v14, v14 quad_perm:[2,3,0,1] row_mask:0xf bank_mask:0xf bound_ctrl:1
	v_add_u32_dpp v2, v2, v2 row_half_mirror row_mask:0xf bank_mask:0xf bound_ctrl:1
	v_add_u32_dpp v13, v13, v13 row_half_mirror row_mask:0xf bank_mask:0xf bound_ctrl:1
	v_cndmask_b32_e64 v0, v0, v1, s[12:13]
	v_cndmask_b32_e64 v1, v10, v11, s[12:13]
	v_dot4c_i32_i8_e32 v44, v43, v39
	v_dot4c_i32_i8_e32 v36, v42, v34
	v_dot4c_i32_i8_e32 v8, v43, v7
	v_add_u32_dpp v6, v48, v48 quad_perm:[1,0,3,2] row_mask:0xf bank_mask:0xf bound_ctrl:1
	v_add_u32_dpp v12, v12, v12 quad_perm:[1,0,3,2] row_mask:0xf bank_mask:0xf bound_ctrl:1
	v_add_u32_dpp v5, v5, v5 quad_perm:[2,3,0,1] row_mask:0xf bank_mask:0xf bound_ctrl:1
	v_add_u32_dpp v15, v15, v15 quad_perm:[2,3,0,1] row_mask:0xf bank_mask:0xf bound_ctrl:1
	v_add_u32_dpp v3, v3, v3 row_half_mirror row_mask:0xf bank_mask:0xf bound_ctrl:1
	v_add_u32_dpp v14, v14, v14 row_half_mirror row_mask:0xf bank_mask:0xf bound_ctrl:1
	v_cndmask_b32_e64 v0, v0, v2, s[14:15]
	v_cndmask_b32_e64 v1, v1, v13, s[14:15]
	v_dot4c_i32_i8_e32 v36, v43, v35
	v_add_u32_dpp v7, v44, v44 quad_perm:[1,0,3,2] row_mask:0xf bank_mask:0xf bound_ctrl:1
	v_add_u32_dpp v8, v8, v8 quad_perm:[1,0,3,2] row_mask:0xf bank_mask:0xf bound_ctrl:1
	v_add_u32_dpp v6, v6, v6 quad_perm:[2,3,0,1] row_mask:0xf bank_mask:0xf bound_ctrl:1
	v_add_u32_dpp v12, v12, v12 quad_perm:[2,3,0,1] row_mask:0xf bank_mask:0xf bound_ctrl:1
	v_add_u32_dpp v5, v5, v5 row_half_mirror row_mask:0xf bank_mask:0xf bound_ctrl:1
	v_add_u32_dpp v15, v15, v15 row_half_mirror row_mask:0xf bank_mask:0xf bound_ctrl:1
	v_cndmask_b32_e64 v0, v0, v3, s[16:17]
	v_cndmask_b32_e64 v1, v1, v14, s[16:17]
	v_add_u32_dpp v9, v36, v36 quad_perm:[1,0,3,2] row_mask:0xf bank_mask:0xf bound_ctrl:1
	v_add_u32_dpp v4, v4, v4 quad_perm:[1,0,3,2] row_mask:0xf bank_mask:0xf bound_ctrl:1
	v_add_u32_dpp v7, v7, v7 quad_perm:[2,3,0,1] row_mask:0xf bank_mask:0xf bound_ctrl:1
	v_add_u32_dpp v8, v8, v8 quad_perm:[2,3,0,1] row_mask:0xf bank_mask:0xf bound_ctrl:1
	v_add_u32_dpp v6, v6, v6 row_half_mirror row_mask:0xf bank_mask:0xf bound_ctrl:1
	v_add_u32_dpp v12, v12, v12 row_half_mirror row_mask:0xf bank_mask:0xf bound_ctrl:1
	v_cndmask_b32_e64 v0, v0, v5, s[18:19]
	v_cndmask_b32_e64 v1, v1, v15, s[18:19]
	s_lshl_b32 s78, s50, 9
	v_add_u32_dpp v9, v9, v9 quad_perm:[2,3,0,1] row_mask:0xf bank_mask:0xf bound_ctrl:1
	v_add_u32_dpp v4, v4, v4 quad_perm:[2,3,0,1] row_mask:0xf bank_mask:0xf bound_ctrl:1
	v_add_u32_dpp v7, v7, v7 row_half_mirror row_mask:0xf bank_mask:0xf bound_ctrl:1
	v_add_u32_dpp v8, v8, v8 row_half_mirror row_mask:0xf bank_mask:0xf bound_ctrl:1
	v_cndmask_b32_e64 v0, v0, v6, s[20:21]
	v_cndmask_b32_e64 v1, v1, v12, s[20:21]
	s_cmp_gt_u32 s76, 15
	v_add_u32_dpp v9, v9, v9 row_half_mirror row_mask:0xf bank_mask:0xf bound_ctrl:1
	v_add_u32_dpp v4, v4, v4 row_half_mirror row_mask:0xf bank_mask:0xf bound_ctrl:1
	v_cndmask_b32_e64 v0, v0, v7, s[22:23]
	v_cndmask_b32_e64 v1, v1, v8, s[22:23]
	s_cselect_b64 s[50:51], -1, 0
	v_cndmask_b32_e64 v0, v0, v9, s[24:25]
	v_cndmask_b32_e64 v1, v1, v4, s[24:25]
	s_mov_b64 s[52:53], -1
	s_and_b64 vcc, exec, s[50:51]
	v_add_u32_e32 v2, s78, v186
	s_cbranch_vccz .LBB0_1381
	ds_add_u32 v2, v0
	ds_add_u32 v2, v1 offset:32
	s_mov_b64 s[52:53], 0

.LBB0_1383:
	s_lshr_b32 s77, s77, 4
	s_lshl_b32 s52, s77, 21
	s_add_u32 s52, s26, s52
	s_addc_u32 s53, s27, 0
	s_min_u32 s76, s76, 0x7c
	s_waitcnt lgkmcnt(1)
	v_mad_u32_u16 v0, v140, s81, v150
	v_mad_u32_u16 v1, v140, s81, v150 op_sel:[1,0,0,0]
	global_load_dwordx4 v[64:67], v0, s[52:53]
	global_load_dwordx4 v[60:63], v1, s[52:53]
	v_mad_u32_u16 v0, v141, s81, v150
	v_mad_u32_u16 v1, v141, s81, v150 op_sel:[1,0,0,0]
	global_load_dwordx4 v[56:59], v0, s[52:53]
	global_load_dwordx4 v[52:55], v1, s[52:53]
	v_mad_u32_u16 v0, v142, s81, v150
	v_mad_u32_u16 v1, v142, s81, v150 op_sel:[1,0,0,0]
	global_load_dwordx4 v[48:51], v0, s[52:53]
	global_load_dwordx4 v[44:47], v1, s[52:53]
	v_mad_u32_u16 v0, v143, s81, v150
	v_mad_u32_u16 v1, v143, s81, v150 op_sel:[1,0,0,0]
	global_load_dwordx4 v[36:39], v0, s[52:53]
	global_load_dwordx4 v[32:35], v1, s[52:53]
	s_waitcnt lgkmcnt(0)
	v_mad_u32_u16 v0, v136, s81, v150
	v_mad_u32_u16 v1, v136, s81, v150 op_sel:[1,0,0,0]
	global_load_dwordx4 v[28:31], v0, s[52:53]
	global_load_dwordx4 v[24:27], v1, s[52:53]
	v_mad_u32_u16 v0, v137, s81, v150
	v_mad_u32_u16 v1, v137, s81, v150 op_sel:[1,0,0,0]
	global_load_dwordx4 v[20:23], v0, s[52:53]
	global_load_dwordx4 v[16:19], v1, s[52:53]
	v_mad_u32_u16 v0, v138, s81, v150
	v_mad_u32_u16 v1, v138, s81, v150 op_sel:[1,0,0,0]
	s_lshl_b32 s40, s40, 10
	global_load_dwordx4 v[12:15], v0, s[52:53]
	global_load_dwordx4 v[8:11], v1, s[52:53]
	v_mad_u32_u16 v0, v139, s81, v150
	v_mad_u32_u16 v1, v139, s81, v150 op_sel:[1,0,0,0]
	v_lshl_add_u64 v[40:41], v[144:145], 0, s[40:41]
	s_lshl_b32 s40, s77, 7
	v_lshl_add_u64 v[40:41], v[40:41], 0, s[40:41]
	global_load_dwordx4 v[4:7], v0, s[52:53]
	s_nop 0
	global_load_dwordx4 v[0:3], v1, s[52:53]
	s_lshl_b32 s40, s76, 7
	global_load_dwordx4 v[40:43], v[40:41], off
	s_addk_i32 s40, 0x180
	s_and_b32 s40, s40, 0x780
	v_lshl_add_u32 v136, s40, 1, v185
	ds_read_b128 v[140:143], v136
	ds_read_b128 v[136:139], v136 offset:16
	v_mov_b32_e32 v146, 0
	s_waitcnt vmcnt(17)
	v_dot4c_i32_i8_e32 v146, v80, v132
	v_mov_b32_e32 v132, 0
	v_dot4c_i32_i8_e32 v132, v80, v128
	v_mov_b32_e32 v128, 0
	v_dot4c_i32_i8_e32 v128, v80, v124
	v_mov_b32_e32 v124, 0
	v_dot4c_i32_i8_e32 v124, v80, v120
	v_mov_b32_e32 v120, 0
	v_dot4c_i32_i8_e32 v120, v80, v116
	v_mov_b32_e32 v116, 0
	v_dot4c_i32_i8_e32 v116, v80, v112
	v_mov_b32_e32 v112, 0
	v_dot4c_i32_i8_e32 v112, v80, v108
	v_mov_b32_e32 v108, 0
	v_dot4c_i32_i8_e32 v108, v80, v104
	v_mov_b32_e32 v104, 0
	v_dot4c_i32_i8_e32 v104, v80, v100
	v_mov_b32_e32 v100, 0
	v_dot4c_i32_i8_e32 v100, v80, v96
	v_mov_b32_e32 v96, 0
	v_dot4c_i32_i8_e32 v96, v80, v92
	v_mov_b32_e32 v92, 0
	v_dot4c_i32_i8_e32 v92, v80, v88
	v_mov_b32_e32 v88, 0
	v_dot4c_i32_i8_e32 v88, v80, v84
	v_mov_b32_e32 v84, 0
	v_dot4c_i32_i8_e32 v132, v81, v129
	v_dot4c_i32_i8_e32 v84, v80, v76
	v_mov_b32_e32 v76, 0
	v_dot4c_i32_i8_e32 v146, v81, v133
	v_dot4c_i32_i8_e32 v132, v82, v130
	v_dot4c_i32_i8_e32 v104, v81, v101
	v_dot4c_i32_i8_e32 v100, v81, v97
	v_dot4c_i32_i8_e32 v76, v80, v72
	v_mov_b32_e32 v72, 0
	v_dot4c_i32_i8_e32 v146, v82, v134
	v_dot4c_i32_i8_e32 v132, v83, v131
	v_dot4c_i32_i8_e32 v128, v81, v125
	v_dot4c_i32_i8_e32 v104, v82, v102
	v_dot4c_i32_i8_e32 v100, v82, v98
	v_dot4c_i32_i8_e32 v96, v81, v93
	v_dot4c_i32_i8_e32 v84, v81, v77
	v_dot4c_i32_i8_e32 v72, v80, v68
	v_dot4c_i32_i8_e32 v146, v83, v135
	v_dot4c_i32_i8_e32 v128, v82, v126
	v_dot4c_i32_i8_e32 v124, v81, v121
	v_dot4c_i32_i8_e32 v120, v81, v117
	v_dot4c_i32_i8_e32 v116, v81, v113
	v_dot4c_i32_i8_e32 v112, v81, v109
	v_dot4c_i32_i8_e32 v108, v81, v105
	v_dot4c_i32_i8_e32 v104, v83, v103
	v_dot4c_i32_i8_e32 v100, v83, v99
	v_dot4c_i32_i8_e32 v96, v82, v94
	v_dot4c_i32_i8_e32 v92, v81, v89
	v_dot4c_i32_i8_e32 v88, v81, v85
	v_dot4c_i32_i8_e32 v84, v82, v78
	v_dot4c_i32_i8_e32 v76, v81, v73
	v_dot4c_i32_i8_e32 v72, v81, v69
	v_add_u32_dpp v69, v132, v132 quad_perm:[1,0,3,2] row_mask:0xf bank_mask:0xf bound_ctrl:1
	v_dot4c_i32_i8_e32 v128, v83, v127
	v_dot4c_i32_i8_e32 v124, v82, v122
	v_dot4c_i32_i8_e32 v120, v82, v118
	v_dot4c_i32_i8_e32 v116, v82, v114
	v_dot4c_i32_i8_e32 v112, v82, v110
	v_dot4c_i32_i8_e32 v108, v82, v106
	v_dot4c_i32_i8_e32 v96, v83, v95
	v_dot4c_i32_i8_e32 v92, v82, v90
	v_dot4c_i32_i8_e32 v88, v82, v86
	v_dot4c_i32_i8_e32 v84, v83, v79
	v_dot4c_i32_i8_e32 v76, v82, v74
	v_dot4c_i32_i8_e32 v72, v82, v70
	v_add_u32_dpp v68, v146, v146 quad_perm:[1,0,3,2] row_mask:0xf bank_mask:0xf bound_ctrl:1
	v_add_u32_dpp v78, v104, v104 quad_perm:[1,0,3,2] row_mask:0xf bank_mask:0xf bound_ctrl:1
	v_add_u32_dpp v79, v100, v100 quad_perm:[1,0,3,2] row_mask:0xf bank_mask:0xf bound_ctrl:1
	v_add_u32_dpp v69, v69, v69 quad_perm:[2,3,0,1] row_mask:0xf bank_mask:0xf bound_ctrl:1
	v_dot4c_i32_i8_e32 v124, v83, v123
	v_dot4c_i32_i8_e32 v120, v83, v119
	v_dot4c_i32_i8_e32 v116, v83, v115
	v_dot4c_i32_i8_e32 v112, v83, v111
	v_dot4c_i32_i8_e32 v108, v83, v107
	v_dot4c_i32_i8_e32 v92, v83, v91
	v_dot4c_i32_i8_e32 v88, v83, v87
	v_dot4c_i32_i8_e32 v76, v83, v75
	v_dot4c_i32_i8_e32 v72, v83, v71
	v_add_u32_dpp v70, v128, v128 quad_perm:[1,0,3,2] row_mask:0xf bank_mask:0xf bound_ctrl:1
	v_add_u32_dpp v80, v96, v96 quad_perm:[1,0,3,2] row_mask:0xf bank_mask:0xf bound_ctrl:1
	v_add_u32_dpp v83, v84, v84 quad_perm:[1,0,3,2] row_mask:0xf bank_mask:0xf bound_ctrl:1
	v_add_u32_dpp v68, v68, v68 quad_perm:[2,3,0,1] row_mask:0xf bank_mask:0xf bound_ctrl:1
	v_add_u32_dpp v78, v78, v78 quad_perm:[2,3,0,1] row_mask:0xf bank_mask:0xf bound_ctrl:1
	v_add_u32_dpp v79, v79, v79 quad_perm:[2,3,0,1] row_mask:0xf bank_mask:0xf bound_ctrl:1
	v_mov_b32_dpp v84, v69 row_half_mirror row_mask:0xf bank_mask:0xf bound_ctrl:1
	v_add_u32_dpp v71, v124, v124 quad_perm:[1,0,3,2] row_mask:0xf bank_mask:0xf bound_ctrl:1
	v_add_u32_dpp v81, v92, v92 quad_perm:[1,0,3,2] row_mask:0xf bank_mask:0xf bound_ctrl:1
	v_add_u32_dpp v70, v70, v70 quad_perm:[2,3,0,1] row_mask:0xf bank_mask:0xf bound_ctrl:1
	v_add_u32_dpp v80, v80, v80 quad_perm:[2,3,0,1] row_mask:0xf bank_mask:0xf bound_ctrl:1
	v_add_u32_dpp v68, v68, v68 row_half_mirror row_mask:0xf bank_mask:0xf bound_ctrl:1
	v_add_u32_dpp v78, v78, v78 row_half_mirror row_mask:0xf bank_mask:0xf bound_ctrl:1
	v_add_u32_dpp v79, v79, v79 row_half_mirror row_mask:0xf bank_mask:0xf bound_ctrl:1
	v_add_u32_e32 v69, v84, v69
	v_add_u32_dpp v73, v120, v120 quad_perm:[1,0,3,2] row_mask:0xf bank_mask:0xf bound_ctrl:1
	v_add_u32_dpp v82, v88, v88 quad_perm:[1,0,3,2] row_mask:0xf bank_mask:0xf bound_ctrl:1
	v_add_u32_dpp v71, v71, v71 quad_perm:[2,3,0,1] row_mask:0xf bank_mask:0xf bound_ctrl:1
	v_add_u32_dpp v81, v81, v81 quad_perm:[2,3,0,1] row_mask:0xf bank_mask:0xf bound_ctrl:1
	v_add_u32_dpp v70, v70, v70 row_half_mirror row_mask:0xf bank_mask:0xf bound_ctrl:1
	v_add_u32_dpp v80, v80, v80 row_half_mirror row_mask:0xf bank_mask:0xf bound_ctrl:1
	v_cndmask_b32_e64 v68, v68, v69, s[12:13]
	v_cndmask_b32_e64 v69, v78, v79, s[12:13]
	v_add_u32_dpp v74, v116, v116 quad_perm:[1,0,3,2] row_mask:0xf bank_mask:0xf bound_ctrl:1
	v_add_u32_dpp v73, v73, v73 quad_perm:[2,3,0,1] row_mask:0xf bank_mask:0xf bound_ctrl:1
	v_add_u32_dpp v82, v82, v82 quad_perm:[2,3,0,1] row_mask:0xf bank_mask:0xf bound_ctrl:1
	v_add_u32_dpp v71, v71, v71 row_half_mirror row_mask:0xf bank_mask:0xf bound_ctrl:1
	v_add_u32_dpp v81, v81, v81 row_half_mirror row_mask:0xf bank_mask:0xf bound_ctrl:1
	v_cndmask_b32_e64 v68, v68, v70, s[14:15]
	v_cndmask_b32_e64 v69, v69, v80, s[14:15]
	v_add_u32_dpp v75, v112, v112 quad_perm:[1,0,3,2] row_mask:0xf bank_mask:0xf bound_ctrl:1
	v_add_u32_dpp v76, v76, v76 quad_perm:[1,0,3,2] row_mask:0xf bank_mask:0xf bound_ctrl:1
	v_add_u32_dpp v74, v74, v74 quad_perm:[2,3,0,1] row_mask:0xf bank_mask:0xf bound_ctrl:1
	v_add_u32_dpp v83, v83, v83 quad_perm:[2,3,0,1] row_mask:0xf bank_mask:0xf bound_ctrl:1
	v_add_u32_dpp v73, v73, v73 row_half_mirror row_mask:0xf bank_mask:0xf bound_ctrl:1
	v_add_u32_dpp v82, v82, v82 row_half_mirror row_mask:0xf bank_mask:0xf bound_ctrl:1
	v_cndmask_b32_e64 v68, v68, v71, s[16:17]
	v_cndmask_b32_e64 v69, v69, v81, s[16:17]
	v_add_u32_dpp v77, v108, v108 quad_perm:[1,0,3,2] row_mask:0xf bank_mask:0xf bound_ctrl:1
	v_add_u32_dpp v72, v72, v72 quad_perm:[1,0,3,2] row_mask:0xf bank_mask:0xf bound_ctrl:1
	v_add_u32_dpp v75, v75, v75 quad_perm:[2,3,0,1] row_mask:0xf bank_mask:0xf bound_ctrl:1
	v_add_u32_dpp v76, v76, v76 quad_perm:[2,3,0,1] row_mask:0xf bank_mask:0xf bound_ctrl:1
	v_add_u32_dpp v74, v74, v74 row_half_mirror row_mask:0xf bank_mask:0xf bound_ctrl:1
	v_add_u32_dpp v83, v83, v83 row_half_mirror row_mask:0xf bank_mask:0xf bound_ctrl:1
	v_cndmask_b32_e64 v68, v68, v73, s[18:19]
	v_cndmask_b32_e64 v69, v69, v82, s[18:19]
	v_add_u32_dpp v77, v77, v77 quad_perm:[2,3,0,1] row_mask:0xf bank_mask:0xf bound_ctrl:1
	v_add_u32_dpp v72, v72, v72 quad_perm:[2,3,0,1] row_mask:0xf bank_mask:0xf bound_ctrl:1
	v_add_u32_dpp v75, v75, v75 row_half_mirror row_mask:0xf bank_mask:0xf bound_ctrl:1
	v_add_u32_dpp v76, v76, v76 row_half_mirror row_mask:0xf bank_mask:0xf bound_ctrl:1
	v_cndmask_b32_e64 v68, v68, v74, s[20:21]
	v_cndmask_b32_e64 v69, v69, v83, s[20:21]
	v_add_u32_dpp v77, v77, v77 row_half_mirror row_mask:0xf bank_mask:0xf bound_ctrl:1
	v_add_u32_dpp v72, v72, v72 row_half_mirror row_mask:0xf bank_mask:0xf bound_ctrl:1
	v_cndmask_b32_e64 v68, v68, v75, s[22:23]
	v_cndmask_b32_e64 v69, v69, v76, s[22:23]
	s_lshl_b32 s40, s45, 9
	v_cndmask_b32_e64 v68, v68, v77, s[24:25]
	v_cndmask_b32_e64 v69, v69, v72, s[24:25]
	s_mov_b64 s[52:53], -1
	s_and_b64 vcc, exec, s[50:51]
	v_add_u32_e32 v70, s40, v186
	s_cbranch_vccz .LBB0_1385
	ds_add_u32 v70, v68
	ds_add_u32 v70, v69 offset:32
	s_mov_b64 s[52:53], 0

.LBB0_1393:
	ds_read_b128 v[0:3], v185
	ds_read_b128 v[10:13], v185 offset:16
	v_lshl_add_u64 v[166:167], s[0:1], 1, v[158:159]
	s_movk_i32 s0, 0x180
	s_mov_b32 s33, -2
	s_waitcnt lgkmcnt(1)
	v_lshlrev_b32_e32 v4, 7, v0
	v_mad_u32_u16 v0, v0, s81, v150 op_sel:[1,0,0,0]
	v_lshlrev_b32_e32 v5, 7, v1
	v_and_or_b32 v14, v4, s68, v150
	v_and_or_b32 v4, v5, s68, v150
	global_load_dwordx4 v[52:55], v0, s[36:37]
	global_load_dwordx4 v[56:59], v4, s[36:37]
	v_mad_u32_u16 v0, v1, s81, v150 op_sel:[1,0,0,0]
	v_mad_u32_u16 v1, v2, s81, v150
	global_load_dwordx4 v[60:63], v0, s[36:37]
	global_load_dwordx4 v[36:39], v1, s[36:37]
	v_mad_u32_u16 v0, v2, s81, v150 op_sel:[1,0,0,0]
	v_mad_u32_u16 v1, v3, s81, v150
	global_load_dwordx4 v[40:43], v0, s[36:37]
	global_load_dwordx4 v[44:47], v1, s[36:37]
	v_mad_u32_u16 v0, v3, s81, v150 op_sel:[1,0,0,0]
	s_waitcnt lgkmcnt(0)
	v_mad_u32_u16 v1, v10, s81, v150
	global_load_dwordx4 v[48:51], v0, s[36:37]
	global_load_dwordx4 v[20:23], v1, s[36:37]
	v_mad_u32_u16 v0, v10, s81, v150 op_sel:[1,0,0,0]
	v_mad_u32_u16 v1, v11, s81, v150
	global_load_dwordx4 v[24:27], v0, s[36:37]
	global_load_dwordx4 v[28:31], v1, s[36:37]
	v_mad_u32_u16 v0, v11, s81, v150 op_sel:[1,0,0,0]
	v_mad_u32_u16 v1, v12, s81, v150
	v_mad_u32_u16 v4, v12, s81, v150 op_sel:[1,0,0,0]
	v_lshlrev_b32_e32 v5, 7, v13
	v_mad_u32_u16 v12, v13, s81, v150 op_sel:[1,0,0,0]
	v_and_or_b32 v8, v5, s68, v150
	global_load_dwordx4 v[32:35], v0, s[36:37]
	s_nop 0
	global_load_dwordx4 v[0:3], v1, s[36:37]
	s_nop 0
	global_load_dwordx4 v[4:7], v4, s[36:37]
	s_nop 0
	global_load_dwordx4 v[8:11], v8, s[36:37]
	s_nop 0
	global_load_dwordx4 v[16:19], v12, s[36:37]
	global_load_dwordx4 v[64:67], v14, s[36:37]
	global_load_dword v220, v[166:167], off
	ds_read_b128 v[12:15], v187
	ds_read_b128 v[72:75], v185 offset:256
	ds_read_b128 v[68:71], v185 offset:272
.LBB0_1394:
	s_add_i32 s1, s33, 2
	s_lshr_b32 s45, s1, 4
	s_lshl_b32 s40, s45, 21
	s_add_u32 s48, s36, s40
	s_waitcnt lgkmcnt(1)
	v_mad_u32_u16 v76, v72, s81, v150
	v_mad_u32_u16 v72, v72, s81, v150 op_sel:[1,0,0,0]
	s_addc_u32 s49, s37, 0
	global_load_dwordx4 v[128:131], v76, s[48:49]
	global_load_dwordx4 v[132:135], v72, s[48:49]
	v_mad_u32_u16 v72, v73, s81, v150
	v_mad_u32_u16 v73, v73, s81, v150 op_sel:[1,0,0,0]
	global_load_dwordx4 v[136:139], v72, s[48:49]
	global_load_dwordx4 v[140:143], v73, s[48:49]
	v_mad_u32_u16 v72, v74, s81, v150
	v_mad_u32_u16 v73, v74, s81, v150 op_sel:[1,0,0,0]
	global_load_dwordx4 v[112:115], v72, s[48:49]
	global_load_dwordx4 v[116:119], v73, s[48:49]
	v_mad_u32_u16 v72, v75, s81, v150
	v_mad_u32_u16 v73, v75, s81, v150 op_sel:[1,0,0,0]
	global_load_dwordx4 v[120:123], v72, s[48:49]
	global_load_dwordx4 v[124:127], v73, s[48:49]
	s_waitcnt lgkmcnt(0)
	v_mad_u32_u16 v72, v68, s81, v150
	v_mad_u32_u16 v68, v68, s81, v150 op_sel:[1,0,0,0]
	global_load_dwordx4 v[96:99], v72, s[48:49]
	global_load_dwordx4 v[100:103], v68, s[48:49]
	v_mad_u32_u16 v68, v69, s81, v150
	v_mad_u32_u16 v69, v69, s81, v150 op_sel:[1,0,0,0]
	global_load_dwordx4 v[104:107], v68, s[48:49]
	global_load_dwordx4 v[108:111], v69, s[48:49]
	v_mad_u32_u16 v68, v70, s81, v150
	v_mad_u32_u16 v69, v70, s81, v150 op_sel:[1,0,0,0]
	global_load_dwordx4 v[76:79], v68, s[48:49]
	global_load_dwordx4 v[80:83], v69, s[48:49]
	v_mad_u32_u16 v68, v71, s81, v150
	v_mad_u32_u16 v69, v71, s81, v150 op_sel:[1,0,0,0]
	global_load_dwordx4 v[84:87], v68, s[48:49]
	global_load_dwordx4 v[88:91], v69, s[48:49]
	s_and_b32 s48, s1, 14
	s_or_b32 s49, s48, 1
	s_lshl_b32 s40, s49, 11
	v_lshl_add_u64 v[68:69], v[166:167], 0, s[40:41]
	s_lshl_b32 s40, s45, 8
	v_lshl_add_u64 v[168:169], v[68:69], 0, s[40:41]
	global_load_dword v221, v[168:169], off
	s_add_i32 s45, s33, 4
	s_and_b32 s33, s45, 14
	v_lshl_add_u32 v68, s49, 7, v187
	ds_read_b128 v[92:95], v68
	v_lshl_add_u32 v68, s33, 8, v185
	ds_read_b128 v[72:75], v68
	ds_read_b128 v[68:71], v68 offset:16
	s_lshr_b32 s45, s45, 4
	s_lshl_b32 s49, s45, 21
	s_waitcnt vmcnt(18)
	v_perm_b32 v145, v52, v64, s71
	v_perm_b32 v52, v52, v64, s72
	v_perm_b32 v64, v60, v56, s71
	v_perm_b32 v56, v60, v56, s72
	v_perm_b32 v60, v64, v145, s73
	v_dot4_i32_i8 v144, v60, v12, 0
	v_perm_b32 v60, v64, v145, s74
	v_mov_b32_e32 v145, 0
	v_dot4c_i32_i8_e32 v145, v60, v12
	v_perm_b32 v60, v56, v52, s73
	v_perm_b32 v52, v56, v52, s74
	v_dot4_i32_i8 v147, v52, v12, 0
	v_perm_b32 v52, v53, v65, s71
	v_perm_b32 v56, v61, v57, s71
	v_dot4_i32_i8 v146, v60, v12, 0
	v_perm_b32 v53, v53, v65, s72
	v_perm_b32 v57, v61, v57, s72
	v_perm_b32 v60, v56, v52, s73
	v_perm_b32 v52, v56, v52, s74
	v_dot4_i32_i8 v223, v52, v12, 0
	v_perm_b32 v52, v57, v53, s73
	v_dot4_i32_i8 v224, v52, v12, 0
	v_perm_b32 v52, v57, v53, s74
	v_dot4_i32_i8 v225, v52, v12, 0
	v_perm_b32 v52, v54, v66, s71
	v_perm_b32 v53, v54, v66, s72
	v_perm_b32 v54, v62, v58, s71
	v_perm_b32 v56, v62, v58, s72
	v_perm_b32 v57, v54, v52, s73
	v_perm_b32 v52, v54, v52, s74
	v_dot4_i32_i8 v227, v52, v12, 0
	v_perm_b32 v52, v56, v53, s73
	v_dot4_i32_i8 v228, v52, v12, 0
	v_perm_b32 v52, v56, v53, s74
	v_perm_b32 v53, v55, v67, s71
	v_perm_b32 v54, v63, v59, s71
	v_dot4_i32_i8 v226, v57, v12, 0
	v_dot4_i32_i8 v229, v52, v12, 0
	v_perm_b32 v55, v55, v67, s72
	v_perm_b32 v56, v63, v59, s72
	v_perm_b32 v57, v54, v53, s73
	v_perm_b32 v54, v54, v53, s74
	v_mov_b32_e32 v53, 0
	v_dot4_i32_i8 v52, v57, v12, 0
	v_dot4c_i32_i8_e32 v53, v54, v12
	v_perm_b32 v57, v56, v55, s73
	v_mov_b32_e32 v54, 0
	v_perm_b32 v56, v56, v55, s74
	v_mov_b32_e32 v55, 0
	v_dot4_i32_i8 v222, v60, v12, 0
	v_dot4c_i32_i8_e32 v54, v57, v12
	v_dot4c_i32_i8_e32 v55, v56, v12
	v_perm_b32 v12, v40, v36, s71
	v_perm_b32 v36, v40, v36, s72
	v_perm_b32 v40, v48, v44, s71
	v_perm_b32 v44, v48, v44, s72
	v_perm_b32 v48, v40, v12, s73
	v_perm_b32 v12, v40, v12, s74
	v_dot4c_i32_i8_e32 v145, v12, v13
	v_perm_b32 v12, v44, v36, s73
	v_dot4c_i32_i8_e32 v146, v12, v13
	v_perm_b32 v12, v44, v36, s74
	v_dot4c_i32_i8_e32 v147, v12, v13
	v_perm_b32 v12, v41, v37, s71
	v_perm_b32 v36, v41, v37, s72
	v_perm_b32 v37, v49, v45, s71
	v_perm_b32 v40, v49, v45, s72
	v_perm_b32 v41, v37, v12, s73
	v_perm_b32 v12, v37, v12, s74
	v_dot4c_i32_i8_e32 v223, v12, v13
	v_perm_b32 v12, v40, v36, s73
	v_dot4c_i32_i8_e32 v224, v12, v13
	v_perm_b32 v12, v40, v36, s74
	v_dot4c_i32_i8_e32 v225, v12, v13
	v_perm_b32 v12, v42, v38, s71
	v_perm_b32 v37, v50, v46, s71
	v_perm_b32 v36, v42, v38, s72
	v_perm_b32 v38, v50, v46, s72
	v_perm_b32 v40, v37, v12, s73
	v_perm_b32 v12, v37, v12, s74
	v_dot4c_i32_i8_e32 v227, v12, v13
	v_perm_b32 v12, v38, v36, s73
	v_dot4c_i32_i8_e32 v228, v12, v13
	v_perm_b32 v12, v38, v36, s74
	v_dot4c_i32_i8_e32 v229, v12, v13
	v_perm_b32 v12, v43, v39, s71
	v_perm_b32 v37, v51, v47, s71
	v_perm_b32 v36, v43, v39, s72
	v_perm_b32 v38, v51, v47, s72
	v_perm_b32 v39, v37, v12, s73
	v_perm_b32 v12, v37, v12, s74
	v_dot4c_i32_i8_e32 v53, v12, v13
	v_perm_b32 v12, v38, v36, s73
	v_dot4c_i32_i8_e32 v54, v12, v13
	v_perm_b32 v12, v38, v36, s74
	v_dot4c_i32_i8_e32 v144, v48, v13
	v_dot4c_i32_i8_e32 v222, v41, v13
	v_dot4c_i32_i8_e32 v226, v40, v13
	v_dot4c_i32_i8_e32 v52, v39, v13
	v_dot4c_i32_i8_e32 v55, v12, v13
	v_perm_b32 v12, v24, v20, s71
	v_perm_b32 v13, v24, v20, s72
	v_perm_b32 v20, v32, v28, s71
	v_perm_b32 v24, v32, v28, s72
	v_perm_b32 v28, v20, v12, s73
	v_perm_b32 v12, v20, v12, s74
	v_dot4c_i32_i8_e32 v145, v12, v14
	v_perm_b32 v12, v24, v13, s73
	v_dot4c_i32_i8_e32 v146, v12, v14
	v_perm_b32 v12, v24, v13, s74
	v_dot4c_i32_i8_e32 v147, v12, v14
	v_perm_b32 v12, v25, v21, s71
	v_perm_b32 v20, v33, v29, s71
	v_perm_b32 v13, v25, v21, s72
	v_perm_b32 v21, v33, v29, s72
	v_perm_b32 v24, v20, v12, s73
	v_perm_b32 v12, v20, v12, s74
	v_dot4c_i32_i8_e32 v223, v12, v14
	v_perm_b32 v12, v21, v13, s73
	v_dot4c_i32_i8_e32 v224, v12, v14
	v_perm_b32 v12, v21, v13, s74
	v_dot4c_i32_i8_e32 v225, v12, v14
	v_perm_b32 v12, v26, v22, s71
	v_perm_b32 v20, v34, v30, s71
	v_perm_b32 v13, v26, v22, s72
	v_perm_b32 v21, v34, v30, s72
	v_perm_b32 v22, v20, v12, s73
	v_perm_b32 v12, v20, v12, s74
	v_dot4c_i32_i8_e32 v227, v12, v14
	v_perm_b32 v12, v21, v13, s73
	v_dot4c_i32_i8_e32 v228, v12, v14
	v_perm_b32 v12, v21, v13, s74
	v_dot4c_i32_i8_e32 v229, v12, v14
	v_perm_b32 v12, v27, v23, s71
	v_perm_b32 v20, v35, v31, s71
	v_dot4c_i32_i8_e32 v226, v22, v14
	v_perm_b32 v13, v27, v23, s72
	v_perm_b32 v21, v35, v31, s72
	v_perm_b32 v22, v20, v12, s73
	v_perm_b32 v12, v20, v12, s74
	v_dot4c_i32_i8_e32 v53, v12, v14
	v_perm_b32 v12, v21, v13, s73
	v_dot4c_i32_i8_e32 v54, v12, v14
	v_perm_b32 v12, v21, v13, s74
	v_dot4c_i32_i8_e32 v55, v12, v14
	v_perm_b32 v12, v4, v0, s71
	v_perm_b32 v0, v4, v0, s72
	v_perm_b32 v4, v16, v8, s71
	v_perm_b32 v8, v16, v8, s72
	v_perm_b32 v13, v4, v12, s73
	v_perm_b32 v4, v4, v12, s74
	v_dot4c_i32_i8_e32 v145, v4, v15
	v_perm_b32 v4, v8, v0, s73
	v_perm_b32 v0, v8, v0, s74
	v_dot4c_i32_i8_e32 v146, v4, v15
	v_dot4c_i32_i8_e32 v147, v0, v15
	v_perm_b32 v0, v5, v1, s71
	v_perm_b32 v4, v17, v9, s71
	v_perm_b32 v1, v5, v1, s72
	v_perm_b32 v5, v17, v9, s72
	v_perm_b32 v8, v4, v0, s73
	v_perm_b32 v0, v4, v0, s74
	v_dot4c_i32_i8_e32 v223, v0, v15
	v_perm_b32 v0, v5, v1, s73
	v_dot4c_i32_i8_e32 v224, v0, v15
	v_perm_b32 v0, v5, v1, s74
	v_dot4c_i32_i8_e32 v225, v0, v15
	v_perm_b32 v0, v6, v2, s71
	v_perm_b32 v1, v6, v2, s72
	v_perm_b32 v2, v18, v10, s71
	v_perm_b32 v4, v18, v10, s72
	v_perm_b32 v5, v2, v0, s73
	v_perm_b32 v0, v2, v0, s74
	v_dot4c_i32_i8_e32 v227, v0, v15
	v_perm_b32 v0, v4, v1, s73
	v_dot4c_i32_i8_e32 v228, v0, v15
	v_perm_b32 v0, v4, v1, s74
	v_dot4c_i32_i8_e32 v229, v0, v15
	v_perm_b32 v0, v7, v3, s71
	v_perm_b32 v2, v19, v11, s71
	v_perm_b32 v1, v7, v3, s72
	v_perm_b32 v3, v19, v11, s72
	v_perm_b32 v4, v2, v0, s73
	v_perm_b32 v0, v2, v0, s74
	v_dot4c_i32_i8_e32 v144, v28, v14
	v_dot4c_i32_i8_e32 v53, v0, v15
	v_perm_b32 v0, v3, v1, s73
	v_dot4c_i32_i8_e32 v222, v24, v14
	v_dot4c_i32_i8_e32 v52, v22, v14
	v_dot4c_i32_i8_e32 v144, v13, v15
	v_dot4c_i32_i8_e32 v54, v0, v15
	v_perm_b32 v0, v3, v1, s74
	v_dot4c_i32_i8_e32 v222, v8, v15
	v_dot4c_i32_i8_e32 v226, v5, v15
	v_dot4c_i32_i8_e32 v52, v4, v15
	v_dot4c_i32_i8_e32 v55, v0, v15
	ds_write_b128 v219, v[144:147] offset:2048
	ds_write_b128 v219, v[222:225] offset:2064
	ds_write_b128 v219, v[226:229] offset:2080
	ds_write_b128 v219, v[52:55] offset:2096
	ds_read2st64_b64 v[0:3], v188 offset0:4 offset1:5
	ds_read2st64_b64 v[4:7], v188 offset0:6 offset1:7
	ds_read2st64_b64 v[8:11], v188 offset0:8 offset1:9
	ds_read2st64_b64 v[12:15], v188 offset0:10 offset1:11
	s_add_u32 s50, s36, s49
	s_addc_u32 s51, s37, 0
	s_lshl_b32 s49, s48, 2
	s_waitcnt lgkmcnt(3)
	v_add_u32_e32 v1, v3, v1
	v_add_u32_e32 v0, v2, v0
	s_add_i32 s49, s64, s49
	s_waitcnt lgkmcnt(2)
	v_add3_u32 v0, v0, v4, v6
	v_add3_u32 v1, v1, v5, v7
	v_mov_b32_e32 v230, s49
	s_waitcnt lgkmcnt(1)
	v_add3_u32 v1, v1, v9, v11
	v_add3_u32 v0, v0, v8, v10
	ds_read_b32 v16, v230
	s_waitcnt lgkmcnt(1)
	v_add3_u32 v0, v0, v12, v14
	v_add3_u32 v1, v1, v13, v15
	v_cvt_f32_i32_e32 v1, v1
	v_cvt_f32_i32_e32 v0, v0
	s_waitcnt vmcnt(17)
	v_lshlrev_b32_e32 v2, 16, v220
	v_and_b32_e32 v3, 0xffff0000, v220
	s_lshl_b32 s48, s48, 11
	s_waitcnt lgkmcnt(0)
	v_pk_fma_f32 v[0:1], v[16:17], v[0:1], v[2:3] op_sel_hi:[0,1,1]
	s_mov_b32 s49, s41
	v_cvt_pk_bf16_f32 v2, v0, v1
	v_lshl_add_u64 v[0:1], v[166:167], 0, s[48:49]
	v_lshl_add_u64 v[0:1], v[0:1], 0, s[40:41]
	global_store_dword v[0:1], v2, off
	v_mad_u32_u16 v0, v72, s81, v150
	v_mad_u32_u16 v1, v72, s81, v150 op_sel:[1,0,0,0]
	global_load_dwordx4 v[64:67], v0, s[50:51]
	global_load_dwordx4 v[52:55], v1, s[50:51]
	v_mad_u32_u16 v0, v73, s81, v150
	v_mad_u32_u16 v1, v73, s81, v150 op_sel:[1,0,0,0]
	global_load_dwordx4 v[56:59], v0, s[50:51]
	global_load_dwordx4 v[60:63], v1, s[50:51]
	v_mad_u32_u16 v0, v74, s81, v150
	v_mad_u32_u16 v1, v74, s81, v150 op_sel:[1,0,0,0]
	global_load_dwordx4 v[36:39], v0, s[50:51]
	global_load_dwordx4 v[40:43], v1, s[50:51]
	v_mad_u32_u16 v0, v75, s81, v150
	v_mad_u32_u16 v1, v75, s81, v150 op_sel:[1,0,0,0]
	global_load_dwordx4 v[44:47], v0, s[50:51]
	global_load_dwordx4 v[48:51], v1, s[50:51]
	v_mad_u32_u16 v0, v68, s81, v150
	v_mad_u32_u16 v1, v68, s81, v150 op_sel:[1,0,0,0]
	global_load_dwordx4 v[20:23], v0, s[50:51]
	global_load_dwordx4 v[24:27], v1, s[50:51]
	v_mad_u32_u16 v0, v69, s81, v150
	v_mad_u32_u16 v1, v69, s81, v150 op_sel:[1,0,0,0]
	global_load_dwordx4 v[28:31], v0, s[50:51]
	global_load_dwordx4 v[32:35], v1, s[50:51]
	v_mad_u32_u16 v0, v70, s81, v150
	v_bfe_u32 v1, v70, 16, 16
	v_mad_u32_u16 v8, v71, s81, v150
	v_bfe_u32 v9, v71, 16, 16
	v_lshl_or_b32 v4, v1, 7, v150
	v_lshl_or_b32 v12, v9, 7, v150
	s_lshl_b32 s40, s33, 11
	global_load_dwordx4 v[0:3], v0, s[50:51]
	s_nop 0
	global_load_dwordx4 v[4:7], v4, s[50:51]
	s_nop 0
	global_load_dwordx4 v[8:11], v8, s[50:51]
	s_nop 0
	global_load_dwordx4 v[16:19], v12, s[50:51]
	v_lshl_add_u64 v[12:13], v[166:167], 0, s[40:41]
	s_lshl_b32 s40, s45, 8
	v_lshl_add_u64 v[12:13], v[12:13], 0, s[40:41]
	global_load_dword v220, v[12:13], off
	v_lshl_add_u32 v12, s33, 7, v187
	s_and_b32 s33, s0, 0x780
	v_lshl_add_u32 v68, s33, 1, v185
	ds_read_b128 v[12:15], v12
	ds_read_b128 v[72:75], v68
	ds_read_b128 v[68:71], v68 offset:16
	s_waitcnt vmcnt(33)
	v_perm_b32 v145, v132, v128, s71
	v_perm_b32 v128, v132, v128, s72
	s_waitcnt vmcnt(31)
	v_perm_b32 v132, v140, v136, s71
	v_perm_b32 v136, v140, v136, s72
	v_perm_b32 v140, v132, v145, s73
	v_perm_b32 v132, v132, v145, s74
	v_mov_b32_e32 v145, 0
	v_dot4c_i32_i8_e32 v145, v132, v92
	v_perm_b32 v132, v136, v128, s73
	v_perm_b32 v128, v136, v128, s74
	v_dot4_i32_i8 v146, v132, v92, 0
	v_dot4_i32_i8 v147, v128, v92, 0
	v_perm_b32 v128, v133, v129, s71
	v_perm_b32 v132, v141, v137, s71
	v_perm_b32 v129, v133, v129, s72
	v_perm_b32 v133, v141, v137, s72
	v_perm_b32 v136, v132, v128, s73
	v_perm_b32 v128, v132, v128, s74
	v_dot4_i32_i8 v223, v128, v92, 0
	v_perm_b32 v128, v133, v129, s73
	v_dot4_i32_i8 v224, v128, v92, 0
	v_perm_b32 v128, v133, v129, s74
	v_dot4_i32_i8 v225, v128, v92, 0
	v_perm_b32 v128, v134, v130, s71
	v_perm_b32 v129, v134, v130, s72
	v_perm_b32 v130, v142, v138, s71
	v_perm_b32 v132, v142, v138, s72
	v_perm_b32 v133, v130, v128, s73
	v_perm_b32 v128, v130, v128, s74
	v_dot4_i32_i8 v227, v128, v92, 0
	v_perm_b32 v128, v132, v129, s73
	v_dot4_i32_i8 v228, v128, v92, 0
	v_perm_b32 v128, v132, v129, s74
	v_perm_b32 v129, v135, v131, s71
	v_perm_b32 v130, v143, v139, s71
	v_dot4_i32_i8 v226, v133, v92, 0
	v_dot4_i32_i8 v229, v128, v92, 0
	v_perm_b32 v131, v135, v131, s72
	v_perm_b32 v132, v143, v139, s72
	v_perm_b32 v133, v130, v129, s73
	v_perm_b32 v130, v130, v129, s74
	v_mov_b32_e32 v129, 0
	v_dot4_i32_i8 v128, v133, v92, 0
	v_dot4c_i32_i8_e32 v129, v130, v92
	v_perm_b32 v133, v132, v131, s73
	v_mov_b32_e32 v130, 0
	v_perm_b32 v132, v132, v131, s74
	v_mov_b32_e32 v131, 0
	v_dot4_i32_i8 v144, v140, v92, 0
	v_dot4_i32_i8 v222, v136, v92, 0
	v_dot4c_i32_i8_e32 v130, v133, v92
	v_dot4c_i32_i8_e32 v131, v132, v92
	s_waitcnt vmcnt(29)
	v_perm_b32 v92, v116, v112, s71
	v_perm_b32 v112, v116, v112, s72
	s_waitcnt vmcnt(27)
	v_perm_b32 v116, v124, v120, s71
	v_perm_b32 v120, v124, v120, s72
	v_perm_b32 v124, v116, v92, s73
	v_perm_b32 v92, v116, v92, s74
	v_dot4c_i32_i8_e32 v145, v92, v93
	v_perm_b32 v92, v120, v112, s73
	v_dot4c_i32_i8_e32 v146, v92, v93
	v_perm_b32 v92, v120, v112, s74
	v_dot4c_i32_i8_e32 v147, v92, v93
	v_perm_b32 v92, v117, v113, s71
	v_perm_b32 v112, v117, v113, s72
	v_perm_b32 v113, v125, v121, s71
	v_perm_b32 v116, v125, v121, s72
	v_perm_b32 v117, v113, v92, s73
	v_perm_b32 v92, v113, v92, s74
	v_dot4c_i32_i8_e32 v223, v92, v93
	v_perm_b32 v92, v116, v112, s73
	v_dot4c_i32_i8_e32 v224, v92, v93
	v_perm_b32 v92, v116, v112, s74
	v_dot4c_i32_i8_e32 v225, v92, v93
	v_perm_b32 v92, v118, v114, s71
	v_perm_b32 v113, v126, v122, s71
	v_perm_b32 v112, v118, v114, s72
	v_perm_b32 v114, v126, v122, s72
	v_perm_b32 v116, v113, v92, s73
	v_perm_b32 v92, v113, v92, s74
	v_dot4c_i32_i8_e32 v227, v92, v93
	v_perm_b32 v92, v114, v112, s73
	v_dot4c_i32_i8_e32 v228, v92, v93
	v_perm_b32 v92, v114, v112, s74
	v_dot4c_i32_i8_e32 v229, v92, v93
	v_perm_b32 v92, v119, v115, s71
	v_perm_b32 v113, v127, v123, s71
	v_perm_b32 v112, v119, v115, s72
	v_perm_b32 v114, v127, v123, s72
	v_perm_b32 v115, v113, v92, s73
	v_perm_b32 v92, v113, v92, s74
	v_dot4c_i32_i8_e32 v129, v92, v93
	v_perm_b32 v92, v114, v112, s73
	v_dot4c_i32_i8_e32 v130, v92, v93
	v_perm_b32 v92, v114, v112, s74
	v_dot4c_i32_i8_e32 v144, v124, v93
	v_dot4c_i32_i8_e32 v222, v117, v93
	v_dot4c_i32_i8_e32 v226, v116, v93
	v_dot4c_i32_i8_e32 v128, v115, v93
	v_dot4c_i32_i8_e32 v131, v92, v93
	s_waitcnt vmcnt(25)
	v_perm_b32 v92, v100, v96, s71
	v_perm_b32 v93, v100, v96, s72
	s_waitcnt vmcnt(23)
	v_perm_b32 v96, v108, v104, s71
	v_perm_b32 v100, v108, v104, s72
	v_perm_b32 v104, v96, v92, s73
	v_perm_b32 v92, v96, v92, s74
	v_dot4c_i32_i8_e32 v145, v92, v94
	v_perm_b32 v92, v100, v93, s73
	v_dot4c_i32_i8_e32 v146, v92, v94
	v_perm_b32 v92, v100, v93, s74
	v_dot4c_i32_i8_e32 v147, v92, v94
	v_perm_b32 v92, v101, v97, s71
	v_perm_b32 v96, v109, v105, s71
	v_perm_b32 v93, v101, v97, s72
	v_perm_b32 v97, v109, v105, s72
	v_perm_b32 v100, v96, v92, s73
	v_perm_b32 v92, v96, v92, s74
	v_dot4c_i32_i8_e32 v223, v92, v94
	v_perm_b32 v92, v97, v93, s73
	v_dot4c_i32_i8_e32 v224, v92, v94
	v_perm_b32 v92, v97, v93, s74
	v_dot4c_i32_i8_e32 v225, v92, v94
	v_perm_b32 v92, v102, v98, s71
	v_perm_b32 v96, v110, v106, s71
	v_perm_b32 v93, v102, v98, s72
	v_perm_b32 v97, v110, v106, s72
	v_perm_b32 v98, v96, v92, s73
	v_perm_b32 v92, v96, v92, s74
	v_dot4c_i32_i8_e32 v227, v92, v94
	v_perm_b32 v92, v97, v93, s73
	v_dot4c_i32_i8_e32 v228, v92, v94
	v_perm_b32 v92, v97, v93, s74
	v_dot4c_i32_i8_e32 v229, v92, v94
	v_perm_b32 v92, v103, v99, s71
	v_perm_b32 v96, v111, v107, s71
	v_dot4c_i32_i8_e32 v226, v98, v94
	v_perm_b32 v93, v103, v99, s72
	v_perm_b32 v97, v111, v107, s72
	v_perm_b32 v98, v96, v92, s73
	v_perm_b32 v92, v96, v92, s74
	v_dot4c_i32_i8_e32 v129, v92, v94
	v_perm_b32 v92, v97, v93, s73
	v_dot4c_i32_i8_e32 v130, v92, v94
	v_perm_b32 v92, v97, v93, s74
	v_dot4c_i32_i8_e32 v131, v92, v94
	s_waitcnt vmcnt(21)
	v_perm_b32 v92, v80, v76, s71
	v_perm_b32 v76, v80, v76, s72
	s_waitcnt vmcnt(19)
	v_perm_b32 v80, v88, v84, s71
	v_perm_b32 v84, v88, v84, s72
	v_perm_b32 v88, v80, v92, s73
	v_perm_b32 v80, v80, v92, s74
	v_dot4c_i32_i8_e32 v145, v80, v95
	v_perm_b32 v80, v84, v76, s73
	v_perm_b32 v76, v84, v76, s74
	v_dot4c_i32_i8_e32 v146, v80, v95
	v_dot4c_i32_i8_e32 v147, v76, v95
	v_perm_b32 v76, v81, v77, s71
	v_perm_b32 v80, v89, v85, s71
	v_perm_b32 v77, v81, v77, s72
	v_perm_b32 v81, v89, v85, s72
	v_perm_b32 v84, v80, v76, s73
	v_perm_b32 v76, v80, v76, s74
	v_dot4c_i32_i8_e32 v223, v76, v95
	v_perm_b32 v76, v81, v77, s73
	v_dot4c_i32_i8_e32 v224, v76, v95
	v_perm_b32 v76, v81, v77, s74
	v_dot4c_i32_i8_e32 v225, v76, v95
	v_perm_b32 v76, v82, v78, s71
	v_perm_b32 v77, v82, v78, s72
	v_perm_b32 v78, v90, v86, s71
	v_perm_b32 v80, v90, v86, s72
	v_perm_b32 v81, v78, v76, s73
	v_perm_b32 v76, v78, v76, s74
	v_dot4c_i32_i8_e32 v227, v76, v95
	v_perm_b32 v76, v80, v77, s73
	v_dot4c_i32_i8_e32 v228, v76, v95
	v_perm_b32 v76, v80, v77, s74
	v_dot4c_i32_i8_e32 v229, v76, v95
	v_perm_b32 v76, v83, v79, s71
	v_perm_b32 v78, v91, v87, s71
	v_perm_b32 v77, v83, v79, s72
	v_perm_b32 v79, v91, v87, s72
	v_perm_b32 v80, v78, v76, s73
	v_perm_b32 v76, v78, v76, s74
	v_dot4c_i32_i8_e32 v144, v104, v94
	v_dot4c_i32_i8_e32 v129, v76, v95
	v_perm_b32 v76, v79, v77, s73
	v_dot4c_i32_i8_e32 v222, v100, v94
	v_dot4c_i32_i8_e32 v128, v98, v94
	v_dot4c_i32_i8_e32 v144, v88, v95
	v_dot4c_i32_i8_e32 v130, v76, v95
	v_perm_b32 v76, v79, v77, s74
	v_dot4c_i32_i8_e32 v222, v84, v95
	v_dot4c_i32_i8_e32 v226, v81, v95
	v_dot4c_i32_i8_e32 v128, v80, v95
	v_dot4c_i32_i8_e32 v131, v76, v95
	ds_write_b128 v219, v[144:147] offset:2048
	ds_write_b128 v219, v[222:225] offset:2064
	ds_write_b128 v219, v[226:229] offset:2080
	ds_write_b128 v219, v[128:131] offset:2096
	ds_read2st64_b64 v[76:79], v188 offset0:4 offset1:5
	ds_read2st64_b64 v[80:83], v188 offset0:6 offset1:7
	ds_read2st64_b64 v[84:87], v188 offset0:8 offset1:9
	ds_read2st64_b64 v[88:91], v188 offset0:10 offset1:11
	ds_read_b32 v92, v230 offset:4
	s_waitcnt lgkmcnt(4)
	v_add_u32_e32 v77, v79, v77
	v_add_u32_e32 v76, v78, v76
	s_waitcnt lgkmcnt(3)
	v_add3_u32 v76, v76, v80, v82
	v_add3_u32 v77, v77, v81, v83
	s_waitcnt lgkmcnt(2)
	v_add3_u32 v77, v77, v85, v87
	v_add3_u32 v76, v76, v84, v86
	s_waitcnt lgkmcnt(1)
	v_add3_u32 v76, v76, v88, v90
	v_add3_u32 v77, v77, v89, v91
	v_cvt_f32_i32_e32 v77, v77
	v_cvt_f32_i32_e32 v76, v76
	s_waitcnt vmcnt(18)
	v_lshlrev_b32_e32 v78, 16, v221
	v_and_b32_e32 v79, 0xffff0000, v221
	s_waitcnt lgkmcnt(0)
	v_pk_fma_f32 v[76:77], v[92:93], v[76:77], v[78:79] op_sel_hi:[0,1,1]
	v_cvt_pk_bf16_f32 v76, v76, v77
	global_store_dword v[168:169], v76, off
	s_addk_i32 s0, 0x100
	s_cmpk_gt_u32 s1, 0x6d
	s_mov_b32 s33, s1
	s_cbranch_scc0 .LBB0_1394
	global_load_dword v228, v[166:167], off sc1
	global_load_dword v227, v[166:167], off offset:256 sc1
	global_load_dword v226, v[166:167], off offset:512 sc1
	global_load_dword v225, v[166:167], off offset:768 sc1
	global_load_dword v224, v[166:167], off offset:1024 sc1
	global_load_dword v223, v[166:167], off offset:1280 sc1
	global_load_dword v222, v[166:167], off offset:1536 sc1
	s_ashr_i32 s45, s44, 31
	s_lshl_b64 s[0:1], s[44:45], 11
	v_lshl_add_u64 v[168:169], v[164:165], 0, s[0:1]
	s_mov_b32 s76, 0
	v_mov_b32_e32 v221, v207
	s_mov_b32 s33, s66
.LBB0_1396:
	v_mad_u32_u16 v76, v72, s81, v150
	v_mad_u32_u16 v72, v72, s81, v150 op_sel:[1,0,0,0]
	global_load_dwordx4 v[128:131], v76, s[42:43]
	global_load_dwordx4 v[132:135], v72, s[42:43]
	v_mad_u32_u16 v72, v73, s81, v150
	v_mad_u32_u16 v73, v73, s81, v150 op_sel:[1,0,0,0]
	global_load_dwordx4 v[136:139], v72, s[42:43]
	global_load_dwordx4 v[140:143], v73, s[42:43]
	v_mad_u32_u16 v72, v74, s81, v150
	v_mad_u32_u16 v73, v74, s81, v150 op_sel:[1,0,0,0]
	global_load_dwordx4 v[112:115], v72, s[42:43]
	global_load_dwordx4 v[116:119], v73, s[42:43]
	v_mad_u32_u16 v72, v75, s81, v150
	v_mad_u32_u16 v73, v75, s81, v150 op_sel:[1,0,0,0]
	global_load_dwordx4 v[120:123], v72, s[42:43]
	global_load_dwordx4 v[124:127], v73, s[42:43]
	v_mad_u32_u16 v72, v68, s81, v150
	v_mad_u32_u16 v68, v68, s81, v150 op_sel:[1,0,0,0]
	global_load_dwordx4 v[96:99], v72, s[42:43]
	global_load_dwordx4 v[100:103], v68, s[42:43]
	v_mad_u32_u16 v68, v69, s81, v150
	v_mad_u32_u16 v69, v69, s81, v150 op_sel:[1,0,0,0]
	global_load_dwordx4 v[104:107], v68, s[42:43]
	global_load_dwordx4 v[108:111], v69, s[42:43]
	v_mad_u32_u16 v68, v70, s81, v150
	v_mad_u32_u16 v69, v70, s81, v150 op_sel:[1,0,0,0]
	global_load_dwordx4 v[80:83], v68, s[42:43]
	global_load_dwordx4 v[84:87], v69, s[42:43]
	v_mad_u32_u16 v68, v71, s81, v150
	v_mad_u32_u16 v69, v71, s81, v150 op_sel:[1,0,0,0]
	global_load_dwordx4 v[88:91], v68, s[42:43]
	global_load_dwordx4 v[92:95], v69, s[42:43]
	ds_read_b128 v[76:79], v221
	global_load_dword v236, v[168:169], off offset:1792
	global_load_dword v235, v[168:169], off sc1
	global_load_dword v234, v[168:169], off offset:256 sc1
	global_load_dword v233, v[168:169], off offset:512 sc1
	global_load_dword v232, v[168:169], off offset:768 sc1
	global_load_dword v231, v[168:169], off offset:1024 sc1
	global_load_dword v230, v[168:169], off offset:1280 sc1
	global_load_dword v229, v[168:169], off offset:1536 sc1
	s_add_i32 s45, s76, 2
	s_cmp_lt_u32 s76, 14
	s_cselect_b32 s52, s45, 15
	v_lshl_add_u32 v68, s52, 8, v185
	s_add_i32 s0, s44, s76
	ds_read_b128 v[72:75], v68
	ds_read_b128 v[68:71], v68 offset:16
	s_ashr_i32 s1, s0, 31
	s_lshl_b64 s[48:49], s[0:1], 12
	s_add_i32 s0, s0, 1
	s_ashr_i32 s1, s0, 31
	s_add_i32 s53, s33, -4
	s_lshl_b32 s40, s52, 11
	s_min_u32 s51, s76, 12
	s_lshl_b64 s[0:1], s[0:1], 12
	s_add_i32 s50, s33, 8
	s_cmp_gt_u32 s76, 13
	s_waitcnt vmcnt(47)
	v_perm_b32 v145, v52, v64, s71
	v_perm_b32 v52, v52, v64, s72
	s_waitcnt vmcnt(45)
	v_perm_b32 v64, v60, v56, s71
	v_perm_b32 v56, v60, v56, s72
	v_perm_b32 v60, v64, v145, s73
	v_dot4_i32_i8 v144, v60, v12, 0
	v_perm_b32 v60, v64, v145, s74
	v_mov_b32_e32 v145, 0
	v_dot4c_i32_i8_e32 v145, v60, v12
	v_perm_b32 v60, v56, v52, s73
	v_perm_b32 v52, v56, v52, s74
	v_dot4_i32_i8 v147, v52, v12, 0
	v_perm_b32 v52, v53, v65, s71
	v_perm_b32 v56, v61, v57, s71
	v_dot4_i32_i8 v146, v60, v12, 0
	v_perm_b32 v53, v53, v65, s72
	v_perm_b32 v57, v61, v57, s72
	v_perm_b32 v60, v56, v52, s73
	v_perm_b32 v52, v56, v52, s74
	v_dot4_i32_i8 v239, v52, v12, 0
	v_perm_b32 v52, v57, v53, s73
	v_dot4_i32_i8 v240, v52, v12, 0
	v_perm_b32 v52, v57, v53, s74
	v_dot4_i32_i8 v241, v52, v12, 0
	v_perm_b32 v52, v54, v66, s71
	v_perm_b32 v53, v54, v66, s72
	v_perm_b32 v54, v62, v58, s71
	v_perm_b32 v56, v62, v58, s72
	v_perm_b32 v57, v54, v52, s73
	v_perm_b32 v52, v54, v52, s74
	v_dot4_i32_i8 v243, v52, v12, 0
	v_perm_b32 v52, v56, v53, s73
	v_dot4_i32_i8 v244, v52, v12, 0
	v_perm_b32 v52, v56, v53, s74
	v_perm_b32 v53, v55, v67, s71
	v_perm_b32 v54, v63, v59, s71
	v_dot4_i32_i8 v242, v57, v12, 0
	v_dot4_i32_i8 v245, v52, v12, 0
	v_perm_b32 v55, v55, v67, s72
	v_perm_b32 v56, v63, v59, s72
	v_perm_b32 v57, v54, v53, s73
	v_perm_b32 v54, v54, v53, s74
	v_mov_b32_e32 v53, 0
	v_dot4_i32_i8 v52, v57, v12, 0
	v_dot4c_i32_i8_e32 v53, v54, v12
	v_perm_b32 v57, v56, v55, s73
	v_mov_b32_e32 v54, 0
	v_perm_b32 v56, v56, v55, s74
	v_mov_b32_e32 v55, 0
	v_dot4_i32_i8 v238, v60, v12, 0
	v_dot4c_i32_i8_e32 v54, v57, v12
	v_dot4c_i32_i8_e32 v55, v56, v12
	s_waitcnt vmcnt(43)
	v_perm_b32 v12, v40, v36, s71
	v_perm_b32 v36, v40, v36, s72
	s_waitcnt vmcnt(41)
	v_perm_b32 v40, v48, v44, s71
	v_perm_b32 v44, v48, v44, s72
	v_perm_b32 v48, v40, v12, s73
	v_perm_b32 v12, v40, v12, s74
	v_dot4c_i32_i8_e32 v145, v12, v13
	v_perm_b32 v12, v44, v36, s73
	v_dot4c_i32_i8_e32 v146, v12, v13
	v_perm_b32 v12, v44, v36, s74
	v_dot4c_i32_i8_e32 v147, v12, v13
	v_perm_b32 v12, v41, v37, s71
	v_perm_b32 v36, v41, v37, s72
	v_perm_b32 v37, v49, v45, s71
	v_perm_b32 v40, v49, v45, s72
	v_perm_b32 v41, v37, v12, s73
	v_perm_b32 v12, v37, v12, s74
	v_dot4c_i32_i8_e32 v239, v12, v13
	v_perm_b32 v12, v40, v36, s73
	v_dot4c_i32_i8_e32 v240, v12, v13
	v_perm_b32 v12, v40, v36, s74
	v_dot4c_i32_i8_e32 v241, v12, v13
	v_perm_b32 v12, v42, v38, s71
	v_perm_b32 v37, v50, v46, s71
	v_perm_b32 v36, v42, v38, s72
	v_perm_b32 v38, v50, v46, s72
	v_perm_b32 v40, v37, v12, s73
	v_perm_b32 v12, v37, v12, s74
	v_dot4c_i32_i8_e32 v243, v12, v13
	v_perm_b32 v12, v38, v36, s73
	v_dot4c_i32_i8_e32 v244, v12, v13
	v_perm_b32 v12, v38, v36, s74
	v_dot4c_i32_i8_e32 v245, v12, v13
	v_perm_b32 v12, v43, v39, s71
	v_perm_b32 v37, v51, v47, s71
	v_perm_b32 v36, v43, v39, s72
	v_perm_b32 v38, v51, v47, s72
	v_perm_b32 v39, v37, v12, s73
	v_perm_b32 v12, v37, v12, s74
	v_dot4c_i32_i8_e32 v53, v12, v13
	v_perm_b32 v12, v38, v36, s73
	v_dot4c_i32_i8_e32 v54, v12, v13
	v_perm_b32 v12, v38, v36, s74
	v_dot4c_i32_i8_e32 v144, v48, v13
	v_dot4c_i32_i8_e32 v238, v41, v13
	v_dot4c_i32_i8_e32 v242, v40, v13
	v_dot4c_i32_i8_e32 v52, v39, v13
	v_dot4c_i32_i8_e32 v55, v12, v13
	s_waitcnt vmcnt(39)
	v_perm_b32 v12, v24, v20, s71
	v_perm_b32 v13, v24, v20, s72
	s_waitcnt vmcnt(37)
	v_perm_b32 v20, v32, v28, s71
	v_perm_b32 v24, v32, v28, s72
	v_perm_b32 v28, v20, v12, s73
	v_perm_b32 v12, v20, v12, s74
	v_dot4c_i32_i8_e32 v145, v12, v14
	v_perm_b32 v12, v24, v13, s73
	v_dot4c_i32_i8_e32 v146, v12, v14
	v_perm_b32 v12, v24, v13, s74
	v_dot4c_i32_i8_e32 v147, v12, v14
	v_perm_b32 v12, v25, v21, s71
	v_perm_b32 v20, v33, v29, s71
	v_perm_b32 v13, v25, v21, s72
	v_perm_b32 v21, v33, v29, s72
	v_perm_b32 v24, v20, v12, s73
	v_perm_b32 v12, v20, v12, s74
	v_dot4c_i32_i8_e32 v239, v12, v14
	v_perm_b32 v12, v21, v13, s73
	v_dot4c_i32_i8_e32 v240, v12, v14
	v_perm_b32 v12, v21, v13, s74
	v_dot4c_i32_i8_e32 v241, v12, v14
	v_perm_b32 v12, v26, v22, s71
	v_perm_b32 v20, v34, v30, s71
	v_perm_b32 v13, v26, v22, s72
	v_perm_b32 v21, v34, v30, s72
	v_perm_b32 v22, v20, v12, s73
	v_perm_b32 v12, v20, v12, s74
	v_dot4c_i32_i8_e32 v243, v12, v14
	v_perm_b32 v12, v21, v13, s73
	v_dot4c_i32_i8_e32 v244, v12, v14
	v_perm_b32 v12, v21, v13, s74
	v_dot4c_i32_i8_e32 v245, v12, v14
	v_perm_b32 v12, v27, v23, s71
	v_perm_b32 v20, v35, v31, s71
	v_dot4c_i32_i8_e32 v242, v22, v14
	v_perm_b32 v13, v27, v23, s72
	v_perm_b32 v21, v35, v31, s72
	v_perm_b32 v22, v20, v12, s73
	v_perm_b32 v12, v20, v12, s74
	v_dot4c_i32_i8_e32 v53, v12, v14
	v_perm_b32 v12, v21, v13, s73
	v_dot4c_i32_i8_e32 v54, v12, v14
	v_perm_b32 v12, v21, v13, s74
	v_dot4c_i32_i8_e32 v55, v12, v14
	s_waitcnt vmcnt(35)
	v_perm_b32 v12, v4, v0, s71
	v_perm_b32 v0, v4, v0, s72
	s_waitcnt vmcnt(33)
	v_perm_b32 v4, v16, v8, s71
	v_perm_b32 v8, v16, v8, s72
	v_perm_b32 v13, v4, v12, s73
	v_perm_b32 v4, v4, v12, s74
	v_dot4c_i32_i8_e32 v145, v4, v15
	v_perm_b32 v4, v8, v0, s73
	v_perm_b32 v0, v8, v0, s74
	v_dot4c_i32_i8_e32 v146, v4, v15
	v_dot4c_i32_i8_e32 v147, v0, v15
	v_perm_b32 v0, v5, v1, s71
	v_perm_b32 v4, v17, v9, s71
	v_perm_b32 v1, v5, v1, s72
	v_perm_b32 v5, v17, v9, s72
	v_perm_b32 v8, v4, v0, s73
	v_perm_b32 v0, v4, v0, s74
	v_dot4c_i32_i8_e32 v239, v0, v15
	v_perm_b32 v0, v5, v1, s73
	v_dot4c_i32_i8_e32 v240, v0, v15
	v_perm_b32 v0, v5, v1, s74
	v_dot4c_i32_i8_e32 v241, v0, v15
	v_perm_b32 v0, v6, v2, s71
	v_perm_b32 v1, v6, v2, s72
	v_perm_b32 v2, v18, v10, s71
	v_perm_b32 v4, v18, v10, s72
	v_perm_b32 v5, v2, v0, s73
	v_perm_b32 v0, v2, v0, s74
	v_dot4c_i32_i8_e32 v243, v0, v15
	v_perm_b32 v0, v4, v1, s73
	v_dot4c_i32_i8_e32 v244, v0, v15
	v_perm_b32 v0, v4, v1, s74
	v_dot4c_i32_i8_e32 v245, v0, v15
	v_perm_b32 v0, v7, v3, s71
	v_perm_b32 v2, v19, v11, s71
	v_perm_b32 v1, v7, v3, s72
	v_perm_b32 v3, v19, v11, s72
	v_perm_b32 v4, v2, v0, s73
	v_perm_b32 v0, v2, v0, s74
	v_dot4c_i32_i8_e32 v144, v28, v14
	v_dot4c_i32_i8_e32 v53, v0, v15
	v_perm_b32 v0, v3, v1, s73
	v_dot4c_i32_i8_e32 v238, v24, v14
	v_dot4c_i32_i8_e32 v52, v22, v14
	v_dot4c_i32_i8_e32 v144, v13, v15
	v_dot4c_i32_i8_e32 v54, v0, v15
	v_perm_b32 v0, v3, v1, s74
	v_dot4c_i32_i8_e32 v238, v8, v15
	v_dot4c_i32_i8_e32 v242, v5, v15
	v_dot4c_i32_i8_e32 v52, v4, v15
	v_dot4c_i32_i8_e32 v55, v0, v15
	ds_write_b128 v219, v[144:147] offset:2048
	ds_write_b128 v219, v[238:241] offset:2064
	ds_write_b128 v219, v[242:245] offset:2080
	ds_write_b128 v219, v[52:55] offset:2096
	ds_read2st64_b64 v[0:3], v188 offset0:4 offset1:5
	ds_read2st64_b64 v[4:7], v188 offset0:6 offset1:7
	s_waitcnt vmcnt(30)
	v_lshlrev_b32_e32 v16, 16, v228
	v_and_b32_e32 v17, 0xffff0000, v228
	s_waitcnt vmcnt(29)
	v_lshlrev_b32_e32 v18, 16, v227
	s_waitcnt lgkmcnt(1)
	v_add_u32_e32 v13, v2, v0
	v_add_u32_e32 v40, v3, v1
	ds_read2st64_b64 v[0:3], v188 offset0:8 offset1:9
	ds_read2st64_b64 v[8:11], v188 offset0:10 offset1:11
	global_load_dwordx2 v[30:31], v[162:163], off
	s_waitcnt lgkmcnt(2)
	v_add3_u32 v4, v13, v4, v6
	v_and_b32_e32 v19, 0xffff0000, v227
	v_pk_mul_f32 v[32:33], v[16:17], v[16:17]
	s_waitcnt lgkmcnt(1)
	v_add3_u32 v0, v4, v0, v2
	v_pk_mul_f32 v[34:35], v[18:19], v[18:19]
	s_waitcnt lgkmcnt(0)
	v_add3_u32 v0, v0, v8, v10
	v_add_f32_e32 v10, v32, v33
	s_waitcnt vmcnt(29)
	v_lshlrev_b32_e32 v20, 16, v226
	v_and_b32_e32 v21, 0xffff0000, v226
	v_add_f32_e32 v10, v34, v10
	v_pk_mul_f32 v[36:37], v[20:21], v[20:21]
	v_add_f32_e32 v10, v35, v10
	s_waitcnt vmcnt(28)
	v_lshlrev_b32_e32 v22, 16, v225
	v_and_b32_e32 v23, 0xffff0000, v225
	v_add_f32_e32 v10, v36, v10
	v_pk_mul_f32 v[38:39], v[22:23], v[22:23]
	v_add3_u32 v5, v40, v5, v7
	v_add_f32_e32 v10, v37, v10
	v_mov_b32_e32 v12, s53
	s_waitcnt vmcnt(27)
	v_lshlrev_b32_e32 v24, 16, v224
	v_and_b32_e32 v25, 0xffff0000, v224
	v_add3_u32 v1, v5, v1, v3
	v_add_f32_e32 v10, v38, v10
	ds_read_b32 v12, v12
	v_add3_u32 v1, v1, v9, v11
	v_pk_mul_f32 v[2:3], v[24:25], v[24:25]
	v_add_f32_e32 v10, v39, v10
	s_waitcnt vmcnt(26)
	v_lshlrev_b32_e32 v26, 16, v223
	v_and_b32_e32 v27, 0xffff0000, v223
	v_cvt_f32_i32_e32 v1, v1
	v_cvt_f32_i32_e32 v0, v0
	v_add_f32_e32 v2, v2, v10
	v_pk_mul_f32 v[4:5], v[26:27], v[26:27]
	v_add_f32_e32 v2, v3, v2
	s_waitcnt vmcnt(25)
	global_load_dwordx2 v[42:43], v[162:163], off offset:512
	global_load_dwordx2 v[44:45], v[162:163], off offset:1024
	global_load_dwordx2 v[46:47], v[162:163], off offset:1536
	global_load_dwordx2 v[48:49], v[162:163], off offset:2048
	global_load_dwordx2 v[50:51], v[162:163], off offset:2560
	global_load_dwordx2 v[56:57], v[162:163], off offset:3072
	global_load_dwordx2 v[58:59], v[162:163], off offset:3584
	v_lshlrev_b32_e32 v28, 16, v222
	v_and_b32_e32 v29, 0xffff0000, v222
	v_add_f32_e32 v2, v4, v2
	v_lshlrev_b32_e32 v14, 16, v220
	v_and_b32_e32 v15, 0xffff0000, v220
	v_pk_mul_f32 v[6:7], v[28:29], v[28:29]
	v_add_f32_e32 v2, v5, v2
	s_waitcnt lgkmcnt(0)
	v_pk_fma_f32 v[0:1], v[12:13], v[0:1], v[14:15] op_sel_hi:[0,1,1]
	v_add_f32_e32 v2, v6, v2
	v_pk_mul_f32 v[8:9], v[0:1], v[0:1]
	v_add_f32_e32 v2, v7, v2
	v_add_f32_e32 v2, v2, v8
	v_add_f32_e32 v2, v9, v2
	ds_bpermute_b32 v3, v189, v2
	s_waitcnt lgkmcnt(0)
	v_add_f32_e32 v2, v2, v3
	ds_bpermute_b32 v3, v190, v2
	s_waitcnt lgkmcnt(0)
	v_add_f32_e32 v2, v2, v3
	ds_bpermute_b32 v3, v191, v2
	s_waitcnt lgkmcnt(0)
	v_add_f32_e32 v2, v2, v3
	ds_bpermute_b32 v3, v192, v2
	s_waitcnt lgkmcnt(0)
	v_add_f32_e32 v2, v2, v3
	ds_bpermute_b32 v3, v193, v2
	s_waitcnt lgkmcnt(0)
	v_add_f32_e32 v2, v2, v3
	ds_bpermute_b32 v3, v194, v2
	s_waitcnt lgkmcnt(0)
	v_add_f32_e32 v2, v2, v3
	v_fmamk_f32 v2, v2, 0x3a800000, v216
	v_mul_f32_e32 v3, 0x4b800000, v2
	v_cmp_gt_f32_e32 vcc, s75, v2
	s_nop 1
	v_cndmask_b32_e32 v2, v2, v3, vcc
	v_rsq_f32_e32 v4, v2
	v_lshl_add_u64 v[2:3], v[160:161], 0, s[48:49]
	v_mul_f32_e32 v5, 0x45800000, v4
	v_cndmask_b32_e32 v4, v4, v5, vcc
	v_pk_mul_f32 v[6:7], v[4:5], v[16:17] op_sel_hi:[0,1]
	s_waitcnt vmcnt(0)
	v_pk_mul_f32 v[6:7], v[30:31], v[6:7]
	global_store_dwordx2 v[2:3], v[6:7], off nt
	v_pk_mul_f32 v[8:9], v[4:5], v[18:19] op_sel_hi:[0,1]
	v_pk_mul_f32 v[0:1], v[0:1], v[4:5] op_sel_hi:[1,0]
	s_nop 0
	v_pk_mul_f32 v[6:7], v[42:43], v[8:9]
	global_store_dwordx2 v[2:3], v[6:7], off offset:512 nt
	v_pk_mul_f32 v[8:9], v[4:5], v[20:21] op_sel_hi:[0,1]
	s_nop 0
	v_pk_mul_f32 v[6:7], v[44:45], v[8:9]
	global_store_dwordx2 v[2:3], v[6:7], off offset:1024 nt
	v_pk_mul_f32 v[8:9], v[4:5], v[22:23] op_sel_hi:[0,1]
	s_nop 0
	v_pk_mul_f32 v[6:7], v[46:47], v[8:9]
	global_store_dwordx2 v[2:3], v[6:7], off offset:1536 nt
	v_pk_mul_f32 v[8:9], v[4:5], v[24:25] op_sel_hi:[0,1]
	s_nop 0
	v_pk_mul_f32 v[6:7], v[48:49], v[8:9]
	global_store_dwordx2 v[2:3], v[6:7], off offset:2048 nt
	v_pk_mul_f32 v[8:9], v[4:5], v[26:27] op_sel_hi:[0,1]
	s_nop 0
	v_pk_mul_f32 v[6:7], v[50:51], v[8:9]
	global_store_dwordx2 v[2:3], v[6:7], off offset:2560 nt
	v_pk_mul_f32 v[8:9], v[4:5], v[28:29] op_sel_hi:[0,1]
	s_nop 0
	v_pk_mul_f32 v[6:7], v[56:57], v[8:9]
	global_store_dwordx2 v[2:3], v[6:7], off offset:3072 nt
	s_nop 0
	v_pk_mul_f32 v[0:1], v[0:1], v[58:59]
	global_store_dwordx2 v[2:3], v[0:1], off offset:3584 nt
	v_mad_u32_u16 v0, v72, s81, v150
	v_mad_u32_u16 v1, v72, s81, v150 op_sel:[1,0,0,0]
	global_load_dwordx4 v[64:67], v0, s[42:43]
	global_load_dwordx4 v[52:55], v1, s[42:43]
	v_mad_u32_u16 v0, v73, s81, v150
	v_mad_u32_u16 v1, v73, s81, v150 op_sel:[1,0,0,0]
	global_load_dwordx4 v[56:59], v0, s[42:43]
	global_load_dwordx4 v[60:63], v1, s[42:43]
	v_mad_u32_u16 v0, v74, s81, v150
	v_mad_u32_u16 v1, v74, s81, v150 op_sel:[1,0,0,0]
	global_load_dwordx4 v[36:39], v0, s[42:43]
	global_load_dwordx4 v[40:43], v1, s[42:43]
	v_mad_u32_u16 v0, v75, s81, v150
	v_mad_u32_u16 v1, v75, s81, v150 op_sel:[1,0,0,0]
	global_load_dwordx4 v[44:47], v0, s[42:43]
	global_load_dwordx4 v[48:51], v1, s[42:43]
	v_mad_u32_u16 v0, v68, s81, v150
	v_mad_u32_u16 v1, v68, s81, v150 op_sel:[1,0,0,0]
	global_load_dwordx4 v[20:23], v0, s[42:43]
	global_load_dwordx4 v[24:27], v1, s[42:43]
	v_mad_u32_u16 v0, v69, s81, v150
	v_mad_u32_u16 v1, v69, s81, v150 op_sel:[1,0,0,0]
	global_load_dwordx4 v[28:31], v0, s[42:43]
	global_load_dwordx4 v[32:35], v1, s[42:43]
	v_mad_u32_u16 v0, v70, s81, v150
	v_bfe_u32 v1, v70, 16, 16
	v_mad_u32_u16 v8, v71, s81, v150
	v_bfe_u32 v9, v71, 16, 16
	v_lshl_or_b32 v4, v1, 7, v150
	v_lshl_or_b32 v12, v9, 7, v150
	global_load_dwordx4 v[0:3], v0, s[42:43]
	s_nop 0
	global_load_dwordx4 v[4:7], v4, s[42:43]
	s_nop 0
	global_load_dwordx4 v[8:11], v8, s[42:43]
	s_nop 0
	global_load_dwordx4 v[16:19], v12, s[42:43]
	v_lshl_add_u32 v12, s52, 7, v187
	v_lshl_add_u64 v[68:69], v[166:167], 0, s[40:41]
	ds_read_b128 v[12:15], v12
	global_load_dword v220, v[68:69], off offset:1792
	global_load_dword v228, v[68:69], off sc1
	global_load_dword v227, v[68:69], off offset:256 sc1
	global_load_dword v226, v[68:69], off offset:512 sc1
	global_load_dword v225, v[68:69], off offset:768 sc1
	global_load_dword v224, v[68:69], off offset:1024 sc1
	global_load_dword v223, v[68:69], off offset:1280 sc1
	global_load_dword v222, v[68:69], off offset:1536 sc1
	v_lshl_add_u32 v68, s51, 8, v185
	ds_read_b128 v[72:75], v68 offset:768
	ds_read_b128 v[68:71], v68 offset:784
	v_perm_b32 v145, v132, v128, s71
	v_perm_b32 v128, v132, v128, s72
	v_perm_b32 v132, v140, v136, s71
	v_perm_b32 v136, v140, v136, s72
	v_perm_b32 v140, v132, v145, s73
	v_perm_b32 v132, v132, v145, s74
	v_mov_b32_e32 v145, 0
	v_dot4c_i32_i8_e32 v145, v132, v76
	v_perm_b32 v132, v136, v128, s73
	v_perm_b32 v128, v136, v128, s74
	v_dot4_i32_i8 v146, v132, v76, 0
	v_dot4_i32_i8 v147, v128, v76, 0
	v_perm_b32 v128, v133, v129, s71
	v_perm_b32 v132, v141, v137, s71
	v_perm_b32 v129, v133, v129, s72
	v_perm_b32 v133, v141, v137, s72
	v_perm_b32 v136, v132, v128, s73
	v_perm_b32 v128, v132, v128, s74
	v_dot4_i32_i8 v239, v128, v76, 0
	v_perm_b32 v128, v133, v129, s73
	v_dot4_i32_i8 v240, v128, v76, 0
	v_perm_b32 v128, v133, v129, s74
	v_dot4_i32_i8 v241, v128, v76, 0
	v_perm_b32 v128, v134, v130, s71
	v_perm_b32 v129, v134, v130, s72
	v_perm_b32 v130, v142, v138, s71
	v_perm_b32 v132, v142, v138, s72
	v_perm_b32 v133, v130, v128, s73
	v_perm_b32 v128, v130, v128, s74
	v_dot4_i32_i8 v243, v128, v76, 0
	v_perm_b32 v128, v132, v129, s73
	v_dot4_i32_i8 v244, v128, v76, 0
	v_perm_b32 v128, v132, v129, s74
	v_perm_b32 v129, v135, v131, s71
	v_perm_b32 v130, v143, v139, s71
	v_dot4_i32_i8 v242, v133, v76, 0
	v_dot4_i32_i8 v245, v128, v76, 0
	v_perm_b32 v131, v135, v131, s72
	v_perm_b32 v132, v143, v139, s72
	v_perm_b32 v133, v130, v129, s73
	v_perm_b32 v130, v130, v129, s74
	v_mov_b32_e32 v129, 0
	v_dot4_i32_i8 v128, v133, v76, 0
	v_dot4c_i32_i8_e32 v129, v130, v76
	v_perm_b32 v133, v132, v131, s73
	v_mov_b32_e32 v130, 0
	v_perm_b32 v132, v132, v131, s74
	v_mov_b32_e32 v131, 0
	v_dot4_i32_i8 v144, v140, v76, 0
	v_dot4_i32_i8 v238, v136, v76, 0
	v_dot4c_i32_i8_e32 v130, v133, v76
	v_dot4c_i32_i8_e32 v131, v132, v76
	v_perm_b32 v76, v116, v112, s71
	v_perm_b32 v112, v116, v112, s72
	v_perm_b32 v116, v124, v120, s71
	v_perm_b32 v120, v124, v120, s72
	v_perm_b32 v124, v116, v76, s73
	v_perm_b32 v76, v116, v76, s74
	v_dot4c_i32_i8_e32 v145, v76, v77
	v_perm_b32 v76, v120, v112, s73
	v_dot4c_i32_i8_e32 v146, v76, v77
	v_perm_b32 v76, v120, v112, s74
	v_dot4c_i32_i8_e32 v147, v76, v77
	v_perm_b32 v76, v117, v113, s71
	v_perm_b32 v112, v117, v113, s72
	v_perm_b32 v113, v125, v121, s71
	v_perm_b32 v116, v125, v121, s72
	v_perm_b32 v117, v113, v76, s73
	v_perm_b32 v76, v113, v76, s74
	v_dot4c_i32_i8_e32 v239, v76, v77
	v_perm_b32 v76, v116, v112, s73
	v_dot4c_i32_i8_e32 v240, v76, v77
	v_perm_b32 v76, v116, v112, s74
	v_dot4c_i32_i8_e32 v241, v76, v77
	v_perm_b32 v76, v118, v114, s71
	v_perm_b32 v113, v126, v122, s71
	v_perm_b32 v112, v118, v114, s72
	v_perm_b32 v114, v126, v122, s72
	v_perm_b32 v116, v113, v76, s73
	v_perm_b32 v76, v113, v76, s74
	v_dot4c_i32_i8_e32 v243, v76, v77
	v_perm_b32 v76, v114, v112, s73
	v_dot4c_i32_i8_e32 v244, v76, v77
	v_perm_b32 v76, v114, v112, s74
	v_dot4c_i32_i8_e32 v245, v76, v77
	v_perm_b32 v76, v119, v115, s71
	v_perm_b32 v113, v127, v123, s71
	v_perm_b32 v112, v119, v115, s72
	v_perm_b32 v114, v127, v123, s72
	v_perm_b32 v115, v113, v76, s73
	v_perm_b32 v76, v113, v76, s74
	v_dot4c_i32_i8_e32 v129, v76, v77
	v_perm_b32 v76, v114, v112, s73
	v_dot4c_i32_i8_e32 v130, v76, v77
	v_perm_b32 v76, v114, v112, s74
	v_dot4c_i32_i8_e32 v144, v124, v77
	v_dot4c_i32_i8_e32 v238, v117, v77
	v_dot4c_i32_i8_e32 v242, v116, v77
	v_dot4c_i32_i8_e32 v128, v115, v77
	v_dot4c_i32_i8_e32 v131, v76, v77
	v_perm_b32 v76, v100, v96, s71
	v_perm_b32 v77, v100, v96, s72
	v_perm_b32 v96, v108, v104, s71
	v_perm_b32 v100, v108, v104, s72
	v_perm_b32 v104, v96, v76, s73
	v_perm_b32 v76, v96, v76, s74
	v_dot4c_i32_i8_e32 v145, v76, v78
	v_perm_b32 v76, v100, v77, s73
	v_dot4c_i32_i8_e32 v146, v76, v78
	v_perm_b32 v76, v100, v77, s74
	v_dot4c_i32_i8_e32 v147, v76, v78
	v_perm_b32 v76, v101, v97, s71
	v_perm_b32 v96, v109, v105, s71
	v_perm_b32 v77, v101, v97, s72
	v_perm_b32 v97, v109, v105, s72
	v_perm_b32 v100, v96, v76, s73
	v_perm_b32 v76, v96, v76, s74
	v_dot4c_i32_i8_e32 v239, v76, v78
	v_perm_b32 v76, v97, v77, s73
	v_dot4c_i32_i8_e32 v240, v76, v78
	v_perm_b32 v76, v97, v77, s74
	v_dot4c_i32_i8_e32 v241, v76, v78
	v_perm_b32 v76, v102, v98, s71
	v_perm_b32 v96, v110, v106, s71
	v_perm_b32 v77, v102, v98, s72
	v_perm_b32 v97, v110, v106, s72
	v_perm_b32 v98, v96, v76, s73
	v_perm_b32 v76, v96, v76, s74
	v_dot4c_i32_i8_e32 v243, v76, v78
	v_perm_b32 v76, v97, v77, s73
	v_dot4c_i32_i8_e32 v244, v76, v78
	v_perm_b32 v76, v97, v77, s74
	v_dot4c_i32_i8_e32 v245, v76, v78
	v_perm_b32 v76, v103, v99, s71
	v_perm_b32 v96, v111, v107, s71
	v_dot4c_i32_i8_e32 v242, v98, v78
	v_perm_b32 v77, v103, v99, s72
	v_perm_b32 v97, v111, v107, s72
	v_perm_b32 v98, v96, v76, s73
	v_perm_b32 v76, v96, v76, s74
	v_dot4c_i32_i8_e32 v129, v76, v78
	v_perm_b32 v76, v97, v77, s73
	v_dot4c_i32_i8_e32 v130, v76, v78
	v_perm_b32 v76, v97, v77, s74
	v_dot4c_i32_i8_e32 v144, v104, v78
	v_dot4c_i32_i8_e32 v238, v100, v78
	v_dot4c_i32_i8_e32 v128, v98, v78
	v_dot4c_i32_i8_e32 v131, v76, v78
	v_perm_b32 v76, v84, v80, s71
	v_perm_b32 v78, v92, v88, s71
	v_perm_b32 v77, v84, v80, s72
	v_perm_b32 v80, v92, v88, s72
	v_perm_b32 v84, v78, v76, s73
	v_perm_b32 v76, v78, v76, s74
	v_dot4c_i32_i8_e32 v145, v76, v79
	v_perm_b32 v76, v80, v77, s73
	v_dot4c_i32_i8_e32 v146, v76, v79
	v_perm_b32 v76, v80, v77, s74
	v_dot4c_i32_i8_e32 v147, v76, v79
	v_perm_b32 v76, v85, v81, s71
	v_perm_b32 v78, v93, v89, s71
	v_perm_b32 v77, v85, v81, s72
	v_perm_b32 v80, v93, v89, s72
	v_perm_b32 v81, v78, v76, s73
	v_perm_b32 v76, v78, v76, s74
	v_dot4c_i32_i8_e32 v239, v76, v79
	v_perm_b32 v76, v80, v77, s73
	v_dot4c_i32_i8_e32 v240, v76, v79
	v_perm_b32 v76, v80, v77, s74
	v_dot4c_i32_i8_e32 v241, v76, v79
	v_perm_b32 v76, v86, v82, s71
	v_perm_b32 v78, v94, v90, s71
	v_dot4c_i32_i8_e32 v238, v81, v79
	v_perm_b32 v77, v86, v82, s72
	v_perm_b32 v80, v94, v90, s72
	v_perm_b32 v81, v78, v76, s73
	v_perm_b32 v76, v78, v76, s74
	v_dot4c_i32_i8_e32 v243, v76, v79
	v_perm_b32 v76, v80, v77, s73
	v_dot4c_i32_i8_e32 v244, v76, v79
	v_perm_b32 v76, v80, v77, s74
	v_dot4c_i32_i8_e32 v245, v76, v79
	v_perm_b32 v76, v87, v83, s71
	v_perm_b32 v78, v95, v91, s71
	v_dot4c_i32_i8_e32 v242, v81, v79
	v_perm_b32 v77, v87, v83, s72
	v_perm_b32 v80, v95, v91, s72
	v_perm_b32 v81, v78, v76, s73
	v_perm_b32 v76, v78, v76, s74
	v_dot4c_i32_i8_e32 v129, v76, v79
	v_perm_b32 v76, v80, v77, s73
	v_dot4c_i32_i8_e32 v144, v84, v79
	v_dot4c_i32_i8_e32 v130, v76, v79
	v_perm_b32 v76, v80, v77, s74
	v_dot4c_i32_i8_e32 v128, v81, v79
	v_dot4c_i32_i8_e32 v131, v76, v79
	ds_write_b128 v219, v[144:147] offset:2048
	ds_write_b128 v219, v[238:241] offset:2064
	ds_write_b128 v219, v[242:245] offset:2080
	ds_write_b128 v219, v[128:131] offset:2096
	ds_read2st64_b64 v[76:79], v188 offset0:4 offset1:5
	ds_read2st64_b64 v[80:83], v188 offset0:6 offset1:7
	v_lshlrev_b32_e32 v92, 16, v235
	v_and_b32_e32 v93, 0xffff0000, v235
	v_lshlrev_b32_e32 v94, 16, v234
	s_waitcnt lgkmcnt(1)
	v_add_u32_e32 v89, v78, v76
	v_add_u32_e32 v116, v79, v77
	ds_read2st64_b64 v[76:79], v188 offset0:8 offset1:9
	ds_read2st64_b64 v[84:87], v188 offset0:10 offset1:11
	global_load_dwordx2 v[106:107], v[162:163], off
	global_load_dwordx2 v[132:133], v[162:163], off offset:512
	global_load_dwordx2 v[134:135], v[162:163], off offset:1024
	global_load_dwordx2 v[136:137], v[162:163], off offset:1536
	global_load_dwordx2 v[138:139], v[162:163], off offset:2048
	global_load_dwordx2 v[140:141], v[162:163], off offset:2560
	global_load_dwordx2 v[142:143], v[162:163], off offset:3072
	global_load_dwordx2 v[126:127], v[162:163], off offset:3584
	s_waitcnt lgkmcnt(2)
	v_add3_u32 v80, v89, v80, v82
	v_and_b32_e32 v95, 0xffff0000, v234
	v_pk_mul_f32 v[108:109], v[92:93], v[92:93]
	s_waitcnt lgkmcnt(1)
	v_add3_u32 v76, v80, v76, v78
	v_pk_mul_f32 v[110:111], v[94:95], v[94:95]
	s_waitcnt lgkmcnt(0)
	v_add3_u32 v76, v76, v84, v86
	v_add_f32_e32 v86, v108, v109
	v_lshlrev_b32_e32 v96, 16, v233
	v_and_b32_e32 v97, 0xffff0000, v233
	v_add_f32_e32 v86, v86, v110
	v_pk_mul_f32 v[112:113], v[96:97], v[96:97]
	v_add_f32_e32 v86, v111, v86
	v_lshlrev_b32_e32 v98, 16, v232
	v_and_b32_e32 v99, 0xffff0000, v232
	v_add_f32_e32 v86, v112, v86
	v_pk_mul_f32 v[114:115], v[98:99], v[98:99]
	v_add3_u32 v81, v116, v81, v83
	v_add_f32_e32 v86, v113, v86
	v_mov_b32_e32 v88, s33
	v_lshlrev_b32_e32 v100, 16, v231
	v_and_b32_e32 v101, 0xffff0000, v231
	v_add3_u32 v77, v81, v77, v79
	v_add_f32_e32 v86, v114, v86
	ds_read_b32 v88, v88
	v_add3_u32 v77, v77, v85, v87
	v_pk_mul_f32 v[78:79], v[100:101], v[100:101]
	v_add_f32_e32 v86, v115, v86
	v_lshlrev_b32_e32 v102, 16, v230
	v_and_b32_e32 v103, 0xffff0000, v230
	v_cvt_f32_i32_e32 v77, v77
	v_cvt_f32_i32_e32 v76, v76
	v_add_f32_e32 v78, v78, v86
	v_pk_mul_f32 v[80:81], v[102:103], v[102:103]
	v_add_f32_e32 v78, v79, v78
	v_lshlrev_b32_e32 v104, 16, v229
	v_and_b32_e32 v105, 0xffff0000, v229
	v_add_f32_e32 v78, v80, v78
	v_lshlrev_b32_e32 v90, 16, v236
	v_and_b32_e32 v91, 0xffff0000, v236
	v_pk_mul_f32 v[82:83], v[104:105], v[104:105]
	v_add_f32_e32 v78, v81, v78
	s_waitcnt lgkmcnt(0)
	v_pk_fma_f32 v[76:77], v[88:89], v[76:77], v[90:91] op_sel_hi:[0,1,1]
	v_add_f32_e32 v78, v82, v78
	v_pk_mul_f32 v[84:85], v[76:77], v[76:77]
	v_add_f32_e32 v78, v83, v78
	v_add_f32_e32 v78, v78, v84
	v_add_f32_e32 v78, v85, v78
	ds_bpermute_b32 v79, v189, v78
	s_waitcnt lgkmcnt(0)
	v_add_f32_e32 v78, v78, v79
	ds_bpermute_b32 v79, v190, v78
	s_waitcnt lgkmcnt(0)
	v_add_f32_e32 v78, v78, v79
	ds_bpermute_b32 v79, v191, v78
	s_waitcnt lgkmcnt(0)
	v_add_f32_e32 v78, v78, v79
	ds_bpermute_b32 v79, v192, v78
	s_waitcnt lgkmcnt(0)
	v_add_f32_e32 v78, v78, v79
	ds_bpermute_b32 v79, v193, v78
	s_waitcnt lgkmcnt(0)
	v_add_f32_e32 v78, v78, v79
	ds_bpermute_b32 v79, v194, v78
	s_waitcnt lgkmcnt(0)
	v_add_f32_e32 v78, v78, v79
	v_fmamk_f32 v78, v78, 0x3a800000, v216
	v_mul_f32_e32 v79, 0x4b800000, v78
	v_cmp_gt_f32_e32 vcc, s75, v78
	s_nop 1
	v_cndmask_b32_e32 v78, v78, v79, vcc
	v_rsq_f32_e32 v80, v78
	v_lshl_add_u64 v[78:79], v[160:161], 0, s[0:1]
	v_mul_f32_e32 v81, 0x45800000, v80
	v_cndmask_b32_e32 v80, v80, v81, vcc
	v_pk_mul_f32 v[82:83], v[80:81], v[92:93] op_sel_hi:[0,1]
	s_waitcnt vmcnt(0)
	v_pk_mul_f32 v[82:83], v[106:107], v[82:83]
	global_store_dwordx2 v[78:79], v[82:83], off nt
	v_pk_mul_f32 v[84:85], v[80:81], v[94:95] op_sel_hi:[0,1]
	v_pk_mul_f32 v[76:77], v[76:77], v[80:81] op_sel_hi:[1,0]
	s_nop 0
	v_pk_mul_f32 v[82:83], v[132:133], v[84:85]
	global_store_dwordx2 v[78:79], v[82:83], off offset:512 nt
	v_pk_mul_f32 v[84:85], v[80:81], v[96:97] op_sel_hi:[0,1]
	s_nop 0
	v_pk_mul_f32 v[82:83], v[134:135], v[84:85]
	global_store_dwordx2 v[78:79], v[82:83], off offset:1024 nt
	v_pk_mul_f32 v[84:85], v[80:81], v[98:99] op_sel_hi:[0,1]
	s_nop 0
	v_pk_mul_f32 v[82:83], v[136:137], v[84:85]
	global_store_dwordx2 v[78:79], v[82:83], off offset:1536 nt
	v_pk_mul_f32 v[84:85], v[80:81], v[100:101] op_sel_hi:[0,1]
	s_nop 0
	v_pk_mul_f32 v[82:83], v[138:139], v[84:85]
	global_store_dwordx2 v[78:79], v[82:83], off offset:2048 nt
	v_pk_mul_f32 v[84:85], v[80:81], v[102:103] op_sel_hi:[0,1]
	s_nop 0
	v_pk_mul_f32 v[82:83], v[140:141], v[84:85]
	global_store_dwordx2 v[78:79], v[82:83], off offset:2560 nt
	v_pk_mul_f32 v[84:85], v[80:81], v[104:105] op_sel_hi:[0,1]
	s_nop 0
	v_pk_mul_f32 v[82:83], v[142:143], v[84:85]
	global_store_dwordx2 v[78:79], v[82:83], off offset:3072 nt
	s_nop 0
	v_pk_mul_f32 v[76:77], v[76:77], v[126:127]
	global_store_dwordx2 v[78:79], v[76:77], off offset:3584 nt
	v_lshl_add_u64 v[168:169], v[168:169], 0, s[46:47]
	v_add_u32_e32 v221, 0x100, v221
	s_mov_b32 s33, s50
	s_mov_b32 s76, s45
	s_cbranch_scc0 .LBB0_1396
	s_add_i32 s48, s80, s30
	s_add_i32 s44, s44, s65
	s_cmpk_gt_i32 s48, 0xff
	s_cbranch_scc0 .LBB0_1345
